# 4-segment + LDS-address GEMM loops with every 32-MFMA cluster on an 8-byte boundary
# speedup vs baseline: 1.0022x; 1.0022x over previous
.LBB0_37:
	s_add_i32 s69, s48, 2
	s_add_u32 s46, s0, 0x100
	s_addc_u32 s47, s1, 0
	s_add_i32 s70, 0, 0x10000
	ds_read_b128 v[140:143], v153
	ds_read_b128 v[144:147], v153 offset:1024
	ds_read_b128 v[148:151], v153 offset:2048
	ds_read_b128 v[168:171], v153 offset:3072
	s_cmp_eq_u32 s12, s48
	s_cselect_b32 s48, s44, s13
	s_cselect_b32 s51, s43, s47
	s_cselect_b32 s50, s42, s46
	s_cselect_b32 s49, s45, s68
	v_lshl_add_u64 v[156:157], s[0:1], 0, v[136:137]
	ds_read_b128 v[172:175], v155
	ds_read_b128 v[176:179], v155 offset:1024
	ds_read_b128 v[180:183], v155 offset:2048
	ds_read_b128 v[184:187], v155 offset:3072
	ds_read_b128 v[188:191], v155 offset:4096
	ds_read_b128 v[192:195], v155 offset:5120
	ds_read_b128 v[196:199], v155 offset:6144
	ds_read_b128 v[224:227], v155 offset:7168
	s_add_i32 m0, s53, 0xc000
	s_nop 0
	global_load_lds_dwordx4 v[156:157], off
	v_lshl_add_u64 v[156:157], s[0:1], 0, v[138:139]
	s_add_i32 m0, s53, 0xe000
	s_nop 0
	global_load_lds_dwordx4 v[156:157], off
	s_add_i32 s71, 0, 0x14000
	s_add_i32 s0, s70, s52
	ds_read_b128 v[228:231], v153 offset:16384
	ds_read_b128 v[232:235], v153 offset:17408
	ds_read_b128 v[236:239], v153 offset:18432
	ds_read_b128 v[240:243], v153 offset:19456
	s_waitcnt lgkmcnt(0)
	s_nop 0
	s_barrier
	v_mfma_f32_16x16x32_bf16 v[126:129], v[140:143], v[172:175], v[126:129]
	v_mfma_f32_16x16x32_bf16 v[122:125], v[148:151], v[172:175], v[122:125]
	v_mfma_f32_16x16x32_bf16 v[110:113], v[140:143], v[180:183], v[110:113]
	v_mfma_f32_16x16x32_bf16 v[106:109], v[148:151], v[180:183], v[106:109]
	v_mfma_f32_16x16x32_bf16 v[94:97], v[140:143], v[188:191], v[94:97]
	v_mfma_f32_16x16x32_bf16 v[90:93], v[148:151], v[188:191], v[90:93]
	v_mfma_f32_16x16x32_bf16 v[78:81], v[140:143], v[196:199], v[78:81]
	v_mfma_f32_16x16x32_bf16 v[74:77], v[148:151], v[196:199], v[74:77]
	v_mfma_f32_16x16x32_bf16 v[126:129], v[144:147], v[176:179], v[126:129]
	v_mfma_f32_16x16x32_bf16 v[122:125], v[168:171], v[176:179], v[122:125]
	v_mfma_f32_16x16x32_bf16 v[110:113], v[144:147], v[184:187], v[110:113]
	v_mfma_f32_16x16x32_bf16 v[106:109], v[168:171], v[184:187], v[106:109]
	v_mfma_f32_16x16x32_bf16 v[94:97], v[144:147], v[192:195], v[94:97]
	v_mfma_f32_16x16x32_bf16 v[90:93], v[168:171], v[192:195], v[90:93]
	v_mfma_f32_16x16x32_bf16 v[78:81], v[144:147], v[224:227], v[78:81]
	v_mfma_f32_16x16x32_bf16 v[74:77], v[168:171], v[224:227], v[74:77]
	v_mfma_f32_16x16x32_bf16 v[118:121], v[228:231], v[172:175], v[118:121]
	v_mfma_f32_16x16x32_bf16 v[114:117], v[236:239], v[172:175], v[114:117]
	v_mfma_f32_16x16x32_bf16 v[102:105], v[228:231], v[180:183], v[102:105]
	v_mfma_f32_16x16x32_bf16 v[98:101], v[236:239], v[180:183], v[98:101]
	v_mfma_f32_16x16x32_bf16 v[86:89], v[228:231], v[188:191], v[86:89]
	v_mfma_f32_16x16x32_bf16 v[82:85], v[236:239], v[188:191], v[82:85]
	v_mfma_f32_16x16x32_bf16 v[70:73], v[228:231], v[196:199], v[70:73]
	v_mfma_f32_16x16x32_bf16 v[66:69], v[236:239], v[196:199], v[66:69]
	v_mfma_f32_16x16x32_bf16 v[118:121], v[232:235], v[176:179], v[118:121]
	v_mfma_f32_16x16x32_bf16 v[114:117], v[240:243], v[176:179], v[114:117]
	v_mfma_f32_16x16x32_bf16 v[102:105], v[232:235], v[184:187], v[102:105]
	v_mfma_f32_16x16x32_bf16 v[98:101], v[240:243], v[184:187], v[98:101]
	v_mfma_f32_16x16x32_bf16 v[86:89], v[232:235], v[192:195], v[86:89]
	v_mfma_f32_16x16x32_bf16 v[82:85], v[240:243], v[192:195], v[82:85]
	v_mfma_f32_16x16x32_bf16 v[70:73], v[232:235], v[224:227], v[70:73]
	v_mfma_f32_16x16x32_bf16 v[66:69], v[240:243], v[224:227], v[66:69]
	s_barrier
	s_mov_b32 m0, s53
	s_add_u32 s78, s50, s94
	s_addc_u32 s79, s51, s95
	ds_read_b128 v[172:175], v155 offset:16384
	ds_read_b128 v[176:179], v155 offset:17408
	ds_read_b128 v[180:183], v155 offset:18432
	ds_read_b128 v[184:187], v155 offset:19456
	ds_read_b128 v[188:191], v155 offset:20480
	ds_read_b128 v[192:195], v155 offset:21504
	ds_read_b128 v[196:199], v155 offset:22528
	ds_read_b128 v[224:227], v155 offset:23552
	global_load_lds_dwordx4 v134, s[50:51]
	s_mov_b32 m0, s54
	s_nop 0
	global_load_lds_dwordx4 v132, s[50:51]
	s_add_u32 s76, s48, s94
	s_addc_u32 s77, s49, s95
	s_mov_b32 m0, s0
	s_nop 0
	global_load_lds_dwordx4 v0, s[48:49]
	s_add_i32 m0, s0, 0x2000
	s_nop 0
	global_load_lds_dwordx4 v130, s[48:49]
	s_add_u32 s0, s48, 0x160000
	s_addc_u32 s1, s49, 0
	s_add_i32 s70, s71, s52
	s_mov_b32 m0, s70
	s_nop 0
	global_load_lds_dwordx4 v0, s[0:1]
	s_add_i32 m0, s70, 0x2000
	s_nop 0
	global_load_lds_dwordx4 v130, s[0:1]
	s_waitcnt vmcnt(6) lgkmcnt(0)
	s_barrier
	v_mfma_f32_16x16x32_bf16 v[62:65], v[140:143], v[172:175], v[62:65]
	v_mfma_f32_16x16x32_bf16 v[58:61], v[148:151], v[172:175], v[58:61]
	v_mfma_f32_16x16x32_bf16 v[46:49], v[140:143], v[180:183], v[46:49]
	v_mfma_f32_16x16x32_bf16 v[42:45], v[148:151], v[180:183], v[42:45]
	v_mfma_f32_16x16x32_bf16 v[30:33], v[140:143], v[188:191], v[30:33]
	v_mfma_f32_16x16x32_bf16 v[26:29], v[148:151], v[188:191], v[26:29]
	v_mfma_f32_16x16x32_bf16 v[14:17], v[140:143], v[196:199], v[14:17]
	v_mfma_f32_16x16x32_bf16 v[10:13], v[148:151], v[196:199], v[10:13]
	v_mfma_f32_16x16x32_bf16 v[62:65], v[144:147], v[176:179], v[62:65]
	v_mfma_f32_16x16x32_bf16 v[58:61], v[168:171], v[176:179], v[58:61]
	v_mfma_f32_16x16x32_bf16 v[46:49], v[144:147], v[184:187], v[46:49]
	v_mfma_f32_16x16x32_bf16 v[42:45], v[168:171], v[184:187], v[42:45]
	v_mfma_f32_16x16x32_bf16 v[30:33], v[144:147], v[192:195], v[30:33]
	v_mfma_f32_16x16x32_bf16 v[26:29], v[168:171], v[192:195], v[26:29]
	v_mfma_f32_16x16x32_bf16 v[14:17], v[144:147], v[224:227], v[14:17]
	v_mfma_f32_16x16x32_bf16 v[10:13], v[168:171], v[224:227], v[10:13]
	v_mfma_f32_16x16x32_bf16 v[54:57], v[228:231], v[172:175], v[54:57]
	v_mfma_f32_16x16x32_bf16 v[50:53], v[236:239], v[172:175], v[50:53]
	v_mfma_f32_16x16x32_bf16 v[38:41], v[228:231], v[180:183], v[38:41]
	v_mfma_f32_16x16x32_bf16 v[34:37], v[236:239], v[180:183], v[34:37]
	v_mfma_f32_16x16x32_bf16 v[22:25], v[228:231], v[188:191], v[22:25]
	v_mfma_f32_16x16x32_bf16 v[18:21], v[236:239], v[188:191], v[18:21]
	v_mfma_f32_16x16x32_bf16 v[6:9], v[228:231], v[196:199], v[6:9]
	v_mfma_f32_16x16x32_bf16 v[2:5], v[236:239], v[196:199], v[2:5]
	v_mfma_f32_16x16x32_bf16 v[54:57], v[232:235], v[176:179], v[54:57]
	v_mfma_f32_16x16x32_bf16 v[50:53], v[240:243], v[176:179], v[50:53]
	v_mfma_f32_16x16x32_bf16 v[38:41], v[232:235], v[184:187], v[38:41]
	v_mfma_f32_16x16x32_bf16 v[34:37], v[240:243], v[184:187], v[34:37]
	v_mfma_f32_16x16x32_bf16 v[22:25], v[232:235], v[192:195], v[22:25]
	v_mfma_f32_16x16x32_bf16 v[18:21], v[240:243], v[192:195], v[18:21]
	v_mfma_f32_16x16x32_bf16 v[6:9], v[232:235], v[224:227], v[6:9]
	v_mfma_f32_16x16x32_bf16 v[2:5], v[240:243], v[224:227], v[2:5]
	s_barrier
	s_add_i32 s70, 0, 0x18000
	ds_read_b128 v[140:143], v153 offset:32768
	ds_read_b128 v[144:147], v153 offset:33792
	ds_read_b128 v[148:151], v153 offset:34816
	ds_read_b128 v[168:171], v153 offset:35840
	s_add_u32 s0, s50, 0x2c0000
	s_addc_u32 s1, s51, 0
	ds_read_b128 v[172:175], v155 offset:32768
	ds_read_b128 v[176:179], v155 offset:33792
	ds_read_b128 v[180:183], v155 offset:34816
	ds_read_b128 v[184:187], v155 offset:35840
	ds_read_b128 v[188:191], v155 offset:36864
	ds_read_b128 v[192:195], v155 offset:37888
	ds_read_b128 v[196:199], v155 offset:38912
	ds_read_b128 v[224:227], v155 offset:39936
	s_mov_b32 m0, s55
	s_nop 0
	global_load_lds_dwordx4 v134, s[0:1]
	s_mov_b32 m0, s56
	s_nop 0
	global_load_lds_dwordx4 v132, s[0:1]
	s_add_i32 s50, 0, 0x1c000
	s_add_i32 s0, s70, s52
	ds_read_b128 v[228:231], v153 offset:49152
	ds_read_b128 v[232:235], v153 offset:50176
	ds_read_b128 v[236:239], v153 offset:51200
	ds_read_b128 v[240:243], v153 offset:52224
	s_waitcnt lgkmcnt(0)
	s_nop 0
	s_barrier
	v_mfma_f32_16x16x32_bf16 v[126:129], v[140:143], v[172:175], v[126:129]
	v_mfma_f32_16x16x32_bf16 v[122:125], v[148:151], v[172:175], v[122:125]
	v_mfma_f32_16x16x32_bf16 v[110:113], v[140:143], v[180:183], v[110:113]
	v_mfma_f32_16x16x32_bf16 v[106:109], v[148:151], v[180:183], v[106:109]
	v_mfma_f32_16x16x32_bf16 v[94:97], v[140:143], v[188:191], v[94:97]
	v_mfma_f32_16x16x32_bf16 v[90:93], v[148:151], v[188:191], v[90:93]
	v_mfma_f32_16x16x32_bf16 v[78:81], v[140:143], v[196:199], v[78:81]
	v_mfma_f32_16x16x32_bf16 v[74:77], v[148:151], v[196:199], v[74:77]
	v_mfma_f32_16x16x32_bf16 v[126:129], v[144:147], v[176:179], v[126:129]
	v_mfma_f32_16x16x32_bf16 v[122:125], v[168:171], v[176:179], v[122:125]
	v_mfma_f32_16x16x32_bf16 v[110:113], v[144:147], v[184:187], v[110:113]
	v_mfma_f32_16x16x32_bf16 v[106:109], v[168:171], v[184:187], v[106:109]
	v_mfma_f32_16x16x32_bf16 v[94:97], v[144:147], v[192:195], v[94:97]
	v_mfma_f32_16x16x32_bf16 v[90:93], v[168:171], v[192:195], v[90:93]
	v_mfma_f32_16x16x32_bf16 v[78:81], v[144:147], v[224:227], v[78:81]
	v_mfma_f32_16x16x32_bf16 v[74:77], v[168:171], v[224:227], v[74:77]
	v_mfma_f32_16x16x32_bf16 v[118:121], v[228:231], v[172:175], v[118:121]
	v_mfma_f32_16x16x32_bf16 v[114:117], v[236:239], v[172:175], v[114:117]
	v_mfma_f32_16x16x32_bf16 v[102:105], v[228:231], v[180:183], v[102:105]
	v_mfma_f32_16x16x32_bf16 v[98:101], v[236:239], v[180:183], v[98:101]
	v_mfma_f32_16x16x32_bf16 v[86:89], v[228:231], v[188:191], v[86:89]
	v_mfma_f32_16x16x32_bf16 v[82:85], v[236:239], v[188:191], v[82:85]
	v_mfma_f32_16x16x32_bf16 v[70:73], v[228:231], v[196:199], v[70:73]
	v_mfma_f32_16x16x32_bf16 v[66:69], v[236:239], v[196:199], v[66:69]
	v_mfma_f32_16x16x32_bf16 v[118:121], v[232:235], v[176:179], v[118:121]
	v_mfma_f32_16x16x32_bf16 v[114:117], v[240:243], v[176:179], v[114:117]
	v_mfma_f32_16x16x32_bf16 v[102:105], v[232:235], v[184:187], v[102:105]
	v_mfma_f32_16x16x32_bf16 v[98:101], v[240:243], v[184:187], v[98:101]
	v_mfma_f32_16x16x32_bf16 v[86:89], v[232:235], v[192:195], v[86:89]
	v_mfma_f32_16x16x32_bf16 v[82:85], v[240:243], v[192:195], v[82:85]
	v_mfma_f32_16x16x32_bf16 v[70:73], v[232:235], v[224:227], v[70:73]
	v_mfma_f32_16x16x32_bf16 v[66:69], v[240:243], v[224:227], v[66:69]
	s_barrier
	s_mov_b32 m0, s57
	ds_read_b128 v[172:175], v155 offset:49152
	ds_read_b128 v[176:179], v155 offset:50176
	ds_read_b128 v[180:183], v155 offset:51200
	ds_read_b128 v[184:187], v155 offset:52224
	ds_read_b128 v[188:191], v155 offset:53248
	ds_read_b128 v[192:195], v155 offset:54272
	ds_read_b128 v[196:199], v155 offset:55296
	ds_read_b128 v[224:227], v155 offset:56320
	global_load_lds_dwordx4 v134, s[78:79]
	s_mov_b32 m0, s58
	s_nop 0
	global_load_lds_dwordx4 v132, s[78:79]
	s_mov_b32 m0, s0
	s_nop 0
	global_load_lds_dwordx4 v0, s[76:77]
	s_add_i32 m0, s0, 0x2000
	s_nop 0
	global_load_lds_dwordx4 v130, s[76:77]
	s_add_u32 s0, s48, 0x160080
	s_addc_u32 s1, s49, 0
	s_add_i32 s48, s50, s52
	s_mov_b32 m0, s48
	s_nop 0
	global_load_lds_dwordx4 v0, s[0:1]
	s_add_i32 m0, s48, 0x2000
	s_nop 0
	global_load_lds_dwordx4 v130, s[0:1]
	s_waitcnt vmcnt(6) lgkmcnt(0)
	s_barrier
	v_mfma_f32_16x16x32_bf16 v[62:65], v[140:143], v[172:175], v[62:65]
	v_mfma_f32_16x16x32_bf16 v[58:61], v[148:151], v[172:175], v[58:61]
	v_mfma_f32_16x16x32_bf16 v[46:49], v[140:143], v[180:183], v[46:49]
	v_mfma_f32_16x16x32_bf16 v[42:45], v[148:151], v[180:183], v[42:45]
	v_mfma_f32_16x16x32_bf16 v[30:33], v[140:143], v[188:191], v[30:33]
	v_mfma_f32_16x16x32_bf16 v[26:29], v[148:151], v[188:191], v[26:29]
	v_mfma_f32_16x16x32_bf16 v[14:17], v[140:143], v[196:199], v[14:17]
	v_mfma_f32_16x16x32_bf16 v[10:13], v[148:151], v[196:199], v[10:13]
	v_mfma_f32_16x16x32_bf16 v[62:65], v[144:147], v[176:179], v[62:65]
	v_mfma_f32_16x16x32_bf16 v[58:61], v[168:171], v[176:179], v[58:61]
	v_mfma_f32_16x16x32_bf16 v[46:49], v[144:147], v[184:187], v[46:49]
	v_mfma_f32_16x16x32_bf16 v[42:45], v[168:171], v[184:187], v[42:45]
	v_mfma_f32_16x16x32_bf16 v[30:33], v[144:147], v[192:195], v[30:33]
	v_mfma_f32_16x16x32_bf16 v[26:29], v[168:171], v[192:195], v[26:29]
	v_mfma_f32_16x16x32_bf16 v[14:17], v[144:147], v[224:227], v[14:17]
	v_mfma_f32_16x16x32_bf16 v[10:13], v[168:171], v[224:227], v[10:13]
	v_mfma_f32_16x16x32_bf16 v[54:57], v[228:231], v[172:175], v[54:57]
	v_mfma_f32_16x16x32_bf16 v[50:53], v[236:239], v[172:175], v[50:53]
	v_mfma_f32_16x16x32_bf16 v[38:41], v[228:231], v[180:183], v[38:41]
	v_mfma_f32_16x16x32_bf16 v[34:37], v[236:239], v[180:183], v[34:37]
	v_mfma_f32_16x16x32_bf16 v[22:25], v[228:231], v[188:191], v[22:25]
	v_mfma_f32_16x16x32_bf16 v[18:21], v[236:239], v[188:191], v[18:21]
	v_mfma_f32_16x16x32_bf16 v[6:9], v[228:231], v[196:199], v[6:9]
	v_mfma_f32_16x16x32_bf16 v[2:5], v[236:239], v[196:199], v[2:5]
	v_mfma_f32_16x16x32_bf16 v[54:57], v[232:235], v[176:179], v[54:57]
	v_mfma_f32_16x16x32_bf16 v[50:53], v[240:243], v[176:179], v[50:53]
	v_mfma_f32_16x16x32_bf16 v[38:41], v[232:235], v[184:187], v[38:41]
	v_mfma_f32_16x16x32_bf16 v[34:37], v[240:243], v[184:187], v[34:37]
	v_mfma_f32_16x16x32_bf16 v[22:25], v[232:235], v[192:195], v[22:25]
	v_mfma_f32_16x16x32_bf16 v[18:21], v[240:243], v[192:195], v[18:21]
	v_mfma_f32_16x16x32_bf16 v[6:9], v[232:235], v[224:227], v[6:9]
	v_mfma_f32_16x16x32_bf16 v[2:5], v[240:243], v[224:227], v[2:5]
	s_barrier
	s_add_u32 s13, s13, 0x100
	s_addc_u32 s68, s68, 0
	s_mov_b64 s[0:1], s[46:47]
	s_mov_b32 s48, s69
	s_cmp_ge_i32 s69, s39
	s_cbranch_scc0 .LBB0_37
	s_cmp_eq_u32 s65, 2
	s_cbranch_scc1 .Lepi10_orig
	v_readlane_b32 s90, v255, 17
	v_readlane_b32 s91, v255, 18
	v_readlane_b32 s96, v255, 19
	v_readlane_b32 s97, v255, 20
	v_lshl_or_b32 v156, s66, 8, v154
	v_lshlrev_b32_e32 v156, 2, v156
	v_lshl_add_u32 v157, v152, 13, v156
	s_lshl_b32 s72, s67, 21
	s_add_u32 s74, s22, s72
	s_addc_u32 s75, s23, 0
	s_add_u32 s76, s22, s72
	s_addc_u32 s77, s23, 0
	s_lshr_b32 s73, s67, 3
	s_mul_i32 s73, s73, 0xc000
	s_add_u32 s73, s73, 0xa000
	s_add_u32 s70, s90, s73
	s_addc_u32 s71, s91, 0
	global_load_dwordx4 v[140:143], v156, s[70:71]
	global_load_dwordx4 v[144:147], v156, s[70:71] offset:64
	global_load_dwordx4 v[148:151], v156, s[70:71] offset:512
	global_load_dwordx4 v[168:171], v156, s[70:71] offset:576
	global_load_dwordx4 v[224:227], v157, s[74:75] nt
	global_load_dwordx4 v[228:231], v157, s[74:75] offset:64 nt
	global_load_dwordx4 v[232:235], v157, s[74:75] offset:512 nt
	global_load_dwordx4 v[236:239], v157, s[74:75] offset:576 nt
	s_add_u32 s74, s74, 0x20000
	s_addc_u32 s75, s75, 0
	global_load_dwordx4 v[240:243], v157, s[74:75] nt
	global_load_dwordx4 v[244:247], v157, s[74:75] offset:64 nt
	s_waitcnt vmcnt(5)
	v_pk_fma_f32 v[128:129], v[128:129], v[142:143], v[226:227]
	v_pk_fma_f32 v[126:127], v[126:127], v[140:141], v[224:225]
	global_store_dwordx4 v157, v[126:129], s[76:77] nt
	global_load_dwordx4 v[224:227], v157, s[74:75] offset:512 nt
	s_waitcnt vmcnt(6)
	v_pk_fma_f32 v[124:125], v[124:125], v[146:147], v[230:231]
	v_pk_fma_f32 v[122:123], v[122:123], v[144:145], v[228:229]
	global_store_dwordx4 v157, v[122:125], s[76:77] offset:64 nt
	global_load_dwordx4 v[228:231], v157, s[74:75] offset:576 nt
	s_waitcnt vmcnt(7)
	v_pk_fma_f32 v[120:121], v[120:121], v[150:151], v[234:235]
	v_pk_fma_f32 v[118:119], v[118:119], v[148:149], v[232:233]
	global_store_dwordx4 v157, v[118:121], s[76:77] offset:512 nt
	s_add_u32 s74, s74, 0x20000
	s_addc_u32 s75, s75, 0
	global_load_dwordx4 v[232:235], v157, s[74:75] nt
	s_waitcnt vmcnt(8)
	v_pk_fma_f32 v[116:117], v[116:117], v[170:171], v[238:239]
	v_pk_fma_f32 v[114:115], v[114:115], v[168:169], v[236:237]
	global_store_dwordx4 v157, v[114:117], s[76:77] offset:576 nt
	global_load_dwordx4 v[236:239], v157, s[74:75] offset:64 nt
	s_add_u32 s76, s76, 0x20000
	s_addc_u32 s77, s77, 0
	s_waitcnt vmcnt(9)
	v_pk_fma_f32 v[112:113], v[112:113], v[142:143], v[242:243]
	v_pk_fma_f32 v[110:111], v[110:111], v[140:141], v[240:241]
	global_store_dwordx4 v157, v[110:113], s[76:77] nt
	global_load_dwordx4 v[240:243], v157, s[74:75] offset:512 nt
	s_waitcnt vmcnt(10)
	v_pk_fma_f32 v[108:109], v[108:109], v[146:147], v[246:247]
	v_pk_fma_f32 v[106:107], v[106:107], v[144:145], v[244:245]
	global_store_dwordx4 v157, v[106:109], s[76:77] offset:64 nt
	global_load_dwordx4 v[244:247], v157, s[74:75] offset:576 nt
	s_waitcnt vmcnt(10)
	v_pk_fma_f32 v[104:105], v[104:105], v[150:151], v[226:227]
	v_pk_fma_f32 v[102:103], v[102:103], v[148:149], v[224:225]
	global_store_dwordx4 v157, v[102:105], s[76:77] offset:512 nt
	s_add_u32 s74, s74, 0x20000
	s_addc_u32 s75, s75, 0
	global_load_dwordx4 v[224:227], v157, s[74:75] nt
	s_waitcnt vmcnt(10)
	v_pk_fma_f32 v[100:101], v[100:101], v[170:171], v[230:231]
	v_pk_fma_f32 v[98:99], v[98:99], v[168:169], v[228:229]
	global_store_dwordx4 v157, v[98:101], s[76:77] offset:576 nt
	global_load_dwordx4 v[228:231], v157, s[74:75] offset:64 nt
	s_add_u32 s76, s76, 0x20000
	s_addc_u32 s77, s77, 0
	s_waitcnt vmcnt(10)
	v_pk_fma_f32 v[96:97], v[96:97], v[142:143], v[234:235]
	v_pk_fma_f32 v[94:95], v[94:95], v[140:141], v[232:233]
	global_store_dwordx4 v157, v[94:97], s[76:77] nt
	global_load_dwordx4 v[232:235], v157, s[74:75] offset:512 nt
	s_waitcnt vmcnt(10)
	v_pk_fma_f32 v[92:93], v[92:93], v[146:147], v[238:239]
	v_pk_fma_f32 v[90:91], v[90:91], v[144:145], v[236:237]
	global_store_dwordx4 v157, v[90:93], s[76:77] offset:64 nt
	global_load_dwordx4 v[236:239], v157, s[74:75] offset:576 nt
	s_waitcnt vmcnt(10)
	v_pk_fma_f32 v[88:89], v[88:89], v[150:151], v[242:243]
	v_pk_fma_f32 v[86:87], v[86:87], v[148:149], v[240:241]
	global_store_dwordx4 v157, v[86:89], s[76:77] offset:512 nt
	s_add_u32 s74, s74, 0xa0000
	s_addc_u32 s75, s75, 0
	global_load_dwordx4 v[240:243], v157, s[74:75] nt
	s_waitcnt vmcnt(10)
	v_pk_fma_f32 v[84:85], v[84:85], v[170:171], v[246:247]
	v_pk_fma_f32 v[82:83], v[82:83], v[168:169], v[244:245]
	global_store_dwordx4 v157, v[82:85], s[76:77] offset:576 nt
	global_load_dwordx4 v[244:247], v157, s[74:75] offset:64 nt
	s_add_u32 s76, s76, 0x20000
	s_addc_u32 s77, s77, 0
	s_waitcnt vmcnt(10)
	v_pk_fma_f32 v[80:81], v[80:81], v[142:143], v[226:227]
	v_pk_fma_f32 v[78:79], v[78:79], v[140:141], v[224:225]
	global_store_dwordx4 v157, v[78:81], s[76:77] nt
	global_load_dwordx4 v[224:227], v157, s[74:75] offset:512 nt
	s_waitcnt vmcnt(10)
	v_pk_fma_f32 v[76:77], v[76:77], v[146:147], v[230:231]
	v_pk_fma_f32 v[74:75], v[74:75], v[144:145], v[228:229]
	global_store_dwordx4 v157, v[74:77], s[76:77] offset:64 nt
	global_load_dwordx4 v[228:231], v157, s[74:75] offset:576 nt
	s_waitcnt vmcnt(10)
	v_pk_fma_f32 v[72:73], v[72:73], v[150:151], v[234:235]
	v_pk_fma_f32 v[70:71], v[70:71], v[148:149], v[232:233]
	global_store_dwordx4 v157, v[70:73], s[76:77] offset:512 nt
	s_add_u32 s74, s74, 0x20000
	s_addc_u32 s75, s75, 0
	global_load_dwordx4 v[232:235], v157, s[74:75] nt
	s_waitcnt vmcnt(10)
	v_pk_fma_f32 v[68:69], v[68:69], v[170:171], v[238:239]
	v_pk_fma_f32 v[66:67], v[66:67], v[168:169], v[236:237]
	global_store_dwordx4 v157, v[66:69], s[76:77] offset:576 nt
	global_load_dwordx4 v[236:239], v157, s[74:75] offset:64 nt
	s_add_u32 s76, s76, 0xa0000
	s_addc_u32 s77, s77, 0
	s_waitcnt vmcnt(10)
	v_pk_fma_f32 v[64:65], v[64:65], v[142:143], v[242:243]
	v_pk_fma_f32 v[62:63], v[62:63], v[140:141], v[240:241]
	global_store_dwordx4 v157, v[62:65], s[76:77] nt
	global_load_dwordx4 v[240:243], v157, s[74:75] offset:512 nt
	s_waitcnt vmcnt(10)
	v_pk_fma_f32 v[60:61], v[60:61], v[146:147], v[246:247]
	v_pk_fma_f32 v[58:59], v[58:59], v[144:145], v[244:245]
	global_store_dwordx4 v157, v[58:61], s[76:77] offset:64 nt
	global_load_dwordx4 v[244:247], v157, s[74:75] offset:576 nt
	s_waitcnt vmcnt(10)
	v_pk_fma_f32 v[56:57], v[56:57], v[150:151], v[226:227]
	v_pk_fma_f32 v[54:55], v[54:55], v[148:149], v[224:225]
	global_store_dwordx4 v157, v[54:57], s[76:77] offset:512 nt
	s_add_u32 s74, s74, 0x20000
	s_addc_u32 s75, s75, 0
	global_load_dwordx4 v[224:227], v157, s[74:75] nt
	s_waitcnt vmcnt(10)
	v_pk_fma_f32 v[52:53], v[52:53], v[170:171], v[230:231]
	v_pk_fma_f32 v[50:51], v[50:51], v[168:169], v[228:229]
	global_store_dwordx4 v157, v[50:53], s[76:77] offset:576 nt
	global_load_dwordx4 v[228:231], v157, s[74:75] offset:64 nt
	s_add_u32 s76, s76, 0x20000
	s_addc_u32 s77, s77, 0
	s_waitcnt vmcnt(10)
	v_pk_fma_f32 v[48:49], v[48:49], v[142:143], v[234:235]
	v_pk_fma_f32 v[46:47], v[46:47], v[140:141], v[232:233]
	global_store_dwordx4 v157, v[46:49], s[76:77] nt
	global_load_dwordx4 v[232:235], v157, s[74:75] offset:512 nt
	s_waitcnt vmcnt(10)
	v_pk_fma_f32 v[44:45], v[44:45], v[146:147], v[238:239]
	v_pk_fma_f32 v[42:43], v[42:43], v[144:145], v[236:237]
	global_store_dwordx4 v157, v[42:45], s[76:77] offset:64 nt
	global_load_dwordx4 v[236:239], v157, s[74:75] offset:576 nt
	s_waitcnt vmcnt(10)
	v_pk_fma_f32 v[40:41], v[40:41], v[150:151], v[242:243]
	v_pk_fma_f32 v[38:39], v[38:39], v[148:149], v[240:241]
	global_store_dwordx4 v157, v[38:41], s[76:77] offset:512 nt
	s_add_u32 s74, s74, 0x20000
	s_addc_u32 s75, s75, 0
	global_load_dwordx4 v[240:243], v157, s[74:75] nt
	s_waitcnt vmcnt(10)
	v_pk_fma_f32 v[36:37], v[36:37], v[170:171], v[246:247]
	v_pk_fma_f32 v[34:35], v[34:35], v[168:169], v[244:245]
	global_store_dwordx4 v157, v[34:37], s[76:77] offset:576 nt
	global_load_dwordx4 v[244:247], v157, s[74:75] offset:64 nt
	s_add_u32 s76, s76, 0x20000
	s_addc_u32 s77, s77, 0
	s_waitcnt vmcnt(10)
	v_pk_fma_f32 v[32:33], v[32:33], v[142:143], v[226:227]
	v_pk_fma_f32 v[30:31], v[30:31], v[140:141], v[224:225]
	global_store_dwordx4 v157, v[30:33], s[76:77] nt
	global_load_dwordx4 v[224:227], v157, s[74:75] offset:512 nt
	s_waitcnt vmcnt(10)
	v_pk_fma_f32 v[28:29], v[28:29], v[146:147], v[230:231]
	v_pk_fma_f32 v[26:27], v[26:27], v[144:145], v[228:229]
	global_store_dwordx4 v157, v[26:29], s[76:77] offset:64 nt
	global_load_dwordx4 v[228:231], v157, s[74:75] offset:576 nt
	s_waitcnt vmcnt(10)
	v_pk_fma_f32 v[24:25], v[24:25], v[150:151], v[234:235]
	v_pk_fma_f32 v[22:23], v[22:23], v[148:149], v[232:233]
	global_store_dwordx4 v157, v[22:25], s[76:77] offset:512 nt
	s_waitcnt vmcnt(9)
	v_pk_fma_f32 v[20:21], v[20:21], v[170:171], v[238:239]
	v_pk_fma_f32 v[18:19], v[18:19], v[168:169], v[236:237]
	global_store_dwordx4 v157, v[18:21], s[76:77] offset:576 nt
	s_add_u32 s76, s76, 0x20000
	s_addc_u32 s77, s77, 0
	s_waitcnt vmcnt(8)
	v_pk_fma_f32 v[16:17], v[16:17], v[142:143], v[242:243]
	v_pk_fma_f32 v[14:15], v[14:15], v[140:141], v[240:241]
	global_store_dwordx4 v157, v[14:17], s[76:77] nt
	s_waitcnt vmcnt(7)
	v_pk_fma_f32 v[12:13], v[12:13], v[146:147], v[246:247]
	v_pk_fma_f32 v[10:11], v[10:11], v[144:145], v[244:245]
	global_store_dwordx4 v157, v[10:13], s[76:77] offset:64 nt
	s_waitcnt vmcnt(6)
	v_pk_fma_f32 v[8:9], v[8:9], v[150:151], v[226:227]
	v_pk_fma_f32 v[6:7], v[6:7], v[148:149], v[224:225]
	global_store_dwordx4 v157, v[6:9], s[76:77] offset:512 nt
	s_waitcnt vmcnt(5)
	v_pk_fma_f32 v[4:5], v[4:5], v[170:171], v[230:231]
	v_pk_fma_f32 v[2:3], v[2:3], v[168:169], v[228:229]
	global_store_dwordx4 v157, v[2:5], s[76:77] offset:576 nt
	s_branch .LBB0_24

.LBB0_234:
	s_add_u32 s39, s46, 0xfff80080
	s_addc_u32 s48, s47, -1
	s_add_i32 s62, 0, 0x10000
	ds_read_b128 v[144:147], v141
	ds_read_b128 v[148:151], v141 offset:1024
	ds_read_b128 v[152:155], v141 offset:2048
	ds_read_b128 v[168:171], v141 offset:3072
	s_cmp_eq_u32 s13, 28
	s_cselect_b32 s51, s43, s48
	s_cselect_b32 s50, s42, s39
	s_cselect_b32 s49, s45, s12
	s_cselect_b32 s48, s44, s1
	ds_read_b128 v[172:175], v143
	ds_read_b128 v[176:179], v143 offset:1024
	ds_read_b128 v[180:183], v143 offset:2048
	ds_read_b128 v[184:187], v143 offset:3072
	ds_read_b128 v[188:191], v143 offset:4096
	ds_read_b128 v[192:195], v143 offset:5120
	ds_read_b128 v[196:199], v143 offset:6144
	ds_read_b128 v[224:227], v143 offset:7168
	s_add_i32 m0, s53, 0xc000
	s_nop 0
	global_load_lds_dwordx4 v136, s[46:47]
	s_add_i32 m0, s53, 0xe000
	s_nop 0
	global_load_lds_dwordx4 v138, s[46:47]
	s_add_i32 s39, 0, 0x14000
	s_add_i32 s62, s62, s52
	ds_read_b128 v[228:231], v141 offset:16384
	ds_read_b128 v[232:235], v141 offset:17408
	ds_read_b128 v[236:239], v141 offset:18432
	ds_read_b128 v[240:243], v141 offset:19456
	s_waitcnt lgkmcnt(0)
	s_barrier
	v_mfma_f32_16x16x32_bf16 v[126:129], v[144:147], v[172:175], v[126:129]
	v_mfma_f32_16x16x32_bf16 v[122:125], v[152:155], v[172:175], v[122:125]
	v_mfma_f32_16x16x32_bf16 v[118:121], v[144:147], v[180:183], v[118:121]
	v_mfma_f32_16x16x32_bf16 v[114:117], v[152:155], v[180:183], v[114:117]
	v_mfma_f32_16x16x32_bf16 v[102:105], v[144:147], v[188:191], v[102:105]
	v_mfma_f32_16x16x32_bf16 v[98:101], v[152:155], v[188:191], v[98:101]
	v_mfma_f32_16x16x32_bf16 v[86:89], v[144:147], v[196:199], v[86:89]
	v_mfma_f32_16x16x32_bf16 v[82:85], v[152:155], v[196:199], v[82:85]
	v_mfma_f32_16x16x32_bf16 v[126:129], v[148:151], v[176:179], v[126:129]
	v_mfma_f32_16x16x32_bf16 v[122:125], v[168:171], v[176:179], v[122:125]
	v_mfma_f32_16x16x32_bf16 v[118:121], v[148:151], v[184:187], v[118:121]
	v_mfma_f32_16x16x32_bf16 v[114:117], v[168:171], v[184:187], v[114:117]
	v_mfma_f32_16x16x32_bf16 v[102:105], v[148:151], v[192:195], v[102:105]
	v_mfma_f32_16x16x32_bf16 v[98:101], v[168:171], v[192:195], v[98:101]
	v_mfma_f32_16x16x32_bf16 v[86:89], v[148:151], v[224:227], v[86:89]
	v_mfma_f32_16x16x32_bf16 v[82:85], v[168:171], v[224:227], v[82:85]
	v_mfma_f32_16x16x32_bf16 v[110:113], v[228:231], v[172:175], v[110:113]
	v_mfma_f32_16x16x32_bf16 v[106:109], v[236:239], v[172:175], v[106:109]
	v_mfma_f32_16x16x32_bf16 v[94:97], v[228:231], v[180:183], v[94:97]
	v_mfma_f32_16x16x32_bf16 v[90:93], v[236:239], v[180:183], v[90:93]
	v_mfma_f32_16x16x32_bf16 v[78:81], v[228:231], v[188:191], v[78:81]
	v_mfma_f32_16x16x32_bf16 v[74:77], v[236:239], v[188:191], v[74:77]
	v_mfma_f32_16x16x32_bf16 v[70:73], v[228:231], v[196:199], v[70:73]
	v_mfma_f32_16x16x32_bf16 v[66:69], v[236:239], v[196:199], v[66:69]
	v_mfma_f32_16x16x32_bf16 v[110:113], v[232:235], v[176:179], v[110:113]
	v_mfma_f32_16x16x32_bf16 v[106:109], v[240:243], v[176:179], v[106:109]
	v_mfma_f32_16x16x32_bf16 v[94:97], v[232:235], v[184:187], v[94:97]
	v_mfma_f32_16x16x32_bf16 v[90:93], v[240:243], v[184:187], v[90:93]
	v_mfma_f32_16x16x32_bf16 v[78:81], v[232:235], v[192:195], v[78:81]
	v_mfma_f32_16x16x32_bf16 v[74:77], v[240:243], v[192:195], v[74:77]
	v_mfma_f32_16x16x32_bf16 v[70:73], v[232:235], v[224:227], v[70:73]
	v_mfma_f32_16x16x32_bf16 v[66:69], v[240:243], v[224:227], v[66:69]
	s_barrier
	s_mov_b32 m0, s53
	s_add_u32 s78, s50, s94
	s_addc_u32 s79, s51, s95
	ds_read_b128 v[172:175], v143 offset:16384
	ds_read_b128 v[176:179], v143 offset:17408
	ds_read_b128 v[180:183], v143 offset:18432
	ds_read_b128 v[184:187], v143 offset:19456
	ds_read_b128 v[188:191], v143 offset:20480
	ds_read_b128 v[192:195], v143 offset:21504
	ds_read_b128 v[196:199], v143 offset:22528
	ds_read_b128 v[224:227], v143 offset:23552
	global_load_lds_dwordx4 v134, s[50:51]
	s_mov_b32 m0, s54
	s_nop 0
	global_load_lds_dwordx4 v132, s[50:51]
	s_add_u32 s76, s48, s94
	s_addc_u32 s77, s49, s95
	s_mov_b32 m0, s62
	s_nop 0
	global_load_lds_dwordx4 v0, s[48:49]
	s_add_i32 m0, s62, 0x2000
	s_nop 0
	global_load_lds_dwordx4 v130, s[48:49]
	s_add_u32 s62, s48, 0x80000
	s_addc_u32 s63, s49, 0
	s_add_i32 s39, s39, s52
	s_mov_b32 m0, s39
	s_nop 0
	global_load_lds_dwordx4 v0, s[62:63]
	s_add_i32 m0, s39, 0x2000
	s_nop 0
	global_load_lds_dwordx4 v130, s[62:63]
	s_waitcnt vmcnt(6) lgkmcnt(0)
	s_barrier
	v_mfma_f32_16x16x32_bf16 v[62:65], v[144:147], v[172:175], v[62:65]
	v_mfma_f32_16x16x32_bf16 v[58:61], v[152:155], v[172:175], v[58:61]
	v_mfma_f32_16x16x32_bf16 v[54:57], v[144:147], v[180:183], v[54:57]
	v_mfma_f32_16x16x32_bf16 v[50:53], v[152:155], v[180:183], v[50:53]
	v_mfma_f32_16x16x32_bf16 v[38:41], v[144:147], v[188:191], v[38:41]
	v_mfma_f32_16x16x32_bf16 v[34:37], v[152:155], v[188:191], v[34:37]
	v_mfma_f32_16x16x32_bf16 v[22:25], v[144:147], v[196:199], v[22:25]
	v_mfma_f32_16x16x32_bf16 v[18:21], v[152:155], v[196:199], v[18:21]
	v_mfma_f32_16x16x32_bf16 v[62:65], v[148:151], v[176:179], v[62:65]
	v_mfma_f32_16x16x32_bf16 v[58:61], v[168:171], v[176:179], v[58:61]
	v_mfma_f32_16x16x32_bf16 v[54:57], v[148:151], v[184:187], v[54:57]
	v_mfma_f32_16x16x32_bf16 v[50:53], v[168:171], v[184:187], v[50:53]
	v_mfma_f32_16x16x32_bf16 v[38:41], v[148:151], v[192:195], v[38:41]
	v_mfma_f32_16x16x32_bf16 v[34:37], v[168:171], v[192:195], v[34:37]
	v_mfma_f32_16x16x32_bf16 v[22:25], v[148:151], v[224:227], v[22:25]
	v_mfma_f32_16x16x32_bf16 v[18:21], v[168:171], v[224:227], v[18:21]
	v_mfma_f32_16x16x32_bf16 v[46:49], v[228:231], v[172:175], v[46:49]
	v_mfma_f32_16x16x32_bf16 v[42:45], v[236:239], v[172:175], v[42:45]
	v_mfma_f32_16x16x32_bf16 v[30:33], v[228:231], v[180:183], v[30:33]
	v_mfma_f32_16x16x32_bf16 v[26:29], v[236:239], v[180:183], v[26:29]
	v_mfma_f32_16x16x32_bf16 v[14:17], v[228:231], v[188:191], v[14:17]
	v_mfma_f32_16x16x32_bf16 v[10:13], v[236:239], v[188:191], v[10:13]
	v_mfma_f32_16x16x32_bf16 v[6:9], v[228:231], v[196:199], v[6:9]
	v_mfma_f32_16x16x32_bf16 v[2:5], v[236:239], v[196:199], v[2:5]
	v_mfma_f32_16x16x32_bf16 v[46:49], v[232:235], v[176:179], v[46:49]
	v_mfma_f32_16x16x32_bf16 v[42:45], v[240:243], v[176:179], v[42:45]
	v_mfma_f32_16x16x32_bf16 v[30:33], v[232:235], v[184:187], v[30:33]
	v_mfma_f32_16x16x32_bf16 v[26:29], v[240:243], v[184:187], v[26:29]
	v_mfma_f32_16x16x32_bf16 v[14:17], v[232:235], v[192:195], v[14:17]
	v_mfma_f32_16x16x32_bf16 v[10:13], v[240:243], v[192:195], v[10:13]
	v_mfma_f32_16x16x32_bf16 v[6:9], v[232:235], v[224:227], v[6:9]
	v_mfma_f32_16x16x32_bf16 v[2:5], v[240:243], v[224:227], v[2:5]
	s_barrier
	s_add_i32 s39, 0, 0x18000
	ds_read_b128 v[144:147], v141 offset:32768
	ds_read_b128 v[148:151], v141 offset:33792
	ds_read_b128 v[152:155], v141 offset:34816
	ds_read_b128 v[168:171], v141 offset:35840
	s_add_u32 s50, s50, 0x80000
	s_addc_u32 s51, s51, 0
	ds_read_b128 v[172:175], v143 offset:32768
	ds_read_b128 v[176:179], v143 offset:33792
	ds_read_b128 v[180:183], v143 offset:34816
	ds_read_b128 v[184:187], v143 offset:35840
	ds_read_b128 v[188:191], v143 offset:36864
	ds_read_b128 v[192:195], v143 offset:37888
	ds_read_b128 v[196:199], v143 offset:38912
	ds_read_b128 v[224:227], v143 offset:39936
	s_mov_b32 m0, s55
	s_nop 0
	global_load_lds_dwordx4 v134, s[50:51]
	s_mov_b32 m0, s56
	s_nop 0
	global_load_lds_dwordx4 v132, s[50:51]
	s_add_i32 s50, 0, 0x1c000
	s_add_i32 s39, s39, s52
	ds_read_b128 v[228:231], v141 offset:49152
	ds_read_b128 v[232:235], v141 offset:50176
	ds_read_b128 v[236:239], v141 offset:51200
	ds_read_b128 v[240:243], v141 offset:52224
	s_waitcnt lgkmcnt(0)
	s_nop 0
	s_barrier
	v_mfma_f32_16x16x32_bf16 v[126:129], v[144:147], v[172:175], v[126:129]
	v_mfma_f32_16x16x32_bf16 v[122:125], v[152:155], v[172:175], v[122:125]
	v_mfma_f32_16x16x32_bf16 v[118:121], v[144:147], v[180:183], v[118:121]
	v_mfma_f32_16x16x32_bf16 v[114:117], v[152:155], v[180:183], v[114:117]
	v_mfma_f32_16x16x32_bf16 v[102:105], v[144:147], v[188:191], v[102:105]
	v_mfma_f32_16x16x32_bf16 v[98:101], v[152:155], v[188:191], v[98:101]
	v_mfma_f32_16x16x32_bf16 v[86:89], v[144:147], v[196:199], v[86:89]
	v_mfma_f32_16x16x32_bf16 v[82:85], v[152:155], v[196:199], v[82:85]
	v_mfma_f32_16x16x32_bf16 v[126:129], v[148:151], v[176:179], v[126:129]
	v_mfma_f32_16x16x32_bf16 v[122:125], v[168:171], v[176:179], v[122:125]
	v_mfma_f32_16x16x32_bf16 v[118:121], v[148:151], v[184:187], v[118:121]
	v_mfma_f32_16x16x32_bf16 v[114:117], v[168:171], v[184:187], v[114:117]
	v_mfma_f32_16x16x32_bf16 v[102:105], v[148:151], v[192:195], v[102:105]
	v_mfma_f32_16x16x32_bf16 v[98:101], v[168:171], v[192:195], v[98:101]
	v_mfma_f32_16x16x32_bf16 v[86:89], v[148:151], v[224:227], v[86:89]
	v_mfma_f32_16x16x32_bf16 v[82:85], v[168:171], v[224:227], v[82:85]
	v_mfma_f32_16x16x32_bf16 v[110:113], v[228:231], v[172:175], v[110:113]
	v_mfma_f32_16x16x32_bf16 v[106:109], v[236:239], v[172:175], v[106:109]
	v_mfma_f32_16x16x32_bf16 v[94:97], v[228:231], v[180:183], v[94:97]
	v_mfma_f32_16x16x32_bf16 v[90:93], v[236:239], v[180:183], v[90:93]
	v_mfma_f32_16x16x32_bf16 v[78:81], v[228:231], v[188:191], v[78:81]
	v_mfma_f32_16x16x32_bf16 v[74:77], v[236:239], v[188:191], v[74:77]
	v_mfma_f32_16x16x32_bf16 v[70:73], v[228:231], v[196:199], v[70:73]
	v_mfma_f32_16x16x32_bf16 v[66:69], v[236:239], v[196:199], v[66:69]
	v_mfma_f32_16x16x32_bf16 v[110:113], v[232:235], v[176:179], v[110:113]
	v_mfma_f32_16x16x32_bf16 v[106:109], v[240:243], v[176:179], v[106:109]
	v_mfma_f32_16x16x32_bf16 v[94:97], v[232:235], v[184:187], v[94:97]
	v_mfma_f32_16x16x32_bf16 v[90:93], v[240:243], v[184:187], v[90:93]
	v_mfma_f32_16x16x32_bf16 v[78:81], v[232:235], v[192:195], v[78:81]
	v_mfma_f32_16x16x32_bf16 v[74:77], v[240:243], v[192:195], v[74:77]
	v_mfma_f32_16x16x32_bf16 v[70:73], v[232:235], v[224:227], v[70:73]
	v_mfma_f32_16x16x32_bf16 v[66:69], v[240:243], v[224:227], v[66:69]
	s_barrier
	s_mov_b32 m0, s57
	ds_read_b128 v[172:175], v143 offset:49152
	ds_read_b128 v[176:179], v143 offset:50176
	ds_read_b128 v[180:183], v143 offset:51200
	ds_read_b128 v[184:187], v143 offset:52224
	ds_read_b128 v[188:191], v143 offset:53248
	ds_read_b128 v[192:195], v143 offset:54272
	ds_read_b128 v[196:199], v143 offset:55296
	ds_read_b128 v[224:227], v143 offset:56320
	global_load_lds_dwordx4 v134, s[78:79]
	s_mov_b32 m0, s58
	s_nop 0
	global_load_lds_dwordx4 v132, s[78:79]
	s_mov_b32 m0, s39
	s_nop 0
	global_load_lds_dwordx4 v0, s[76:77]
	s_add_i32 m0, s39, 0x2000
	s_nop 0
	global_load_lds_dwordx4 v130, s[76:77]
	s_add_u32 s48, s48, 0x80080
	s_addc_u32 s49, s49, 0
	s_add_i32 s39, s50, s52
	s_mov_b32 m0, s39
	s_nop 0
	global_load_lds_dwordx4 v0, s[48:49]
	s_add_i32 m0, s39, 0x2000
	s_nop 0
	global_load_lds_dwordx4 v130, s[48:49]
	s_waitcnt vmcnt(6) lgkmcnt(0)
	s_barrier
	v_mfma_f32_16x16x32_bf16 v[62:65], v[144:147], v[172:175], v[62:65]
	v_mfma_f32_16x16x32_bf16 v[58:61], v[152:155], v[172:175], v[58:61]
	v_mfma_f32_16x16x32_bf16 v[54:57], v[144:147], v[180:183], v[54:57]
	v_mfma_f32_16x16x32_bf16 v[50:53], v[152:155], v[180:183], v[50:53]
	v_mfma_f32_16x16x32_bf16 v[38:41], v[144:147], v[188:191], v[38:41]
	v_mfma_f32_16x16x32_bf16 v[34:37], v[152:155], v[188:191], v[34:37]
	v_mfma_f32_16x16x32_bf16 v[22:25], v[144:147], v[196:199], v[22:25]
	v_mfma_f32_16x16x32_bf16 v[18:21], v[152:155], v[196:199], v[18:21]
	v_mfma_f32_16x16x32_bf16 v[62:65], v[148:151], v[176:179], v[62:65]
	v_mfma_f32_16x16x32_bf16 v[58:61], v[168:171], v[176:179], v[58:61]
	v_mfma_f32_16x16x32_bf16 v[54:57], v[148:151], v[184:187], v[54:57]
	v_mfma_f32_16x16x32_bf16 v[50:53], v[168:171], v[184:187], v[50:53]
	v_mfma_f32_16x16x32_bf16 v[38:41], v[148:151], v[192:195], v[38:41]
	v_mfma_f32_16x16x32_bf16 v[34:37], v[168:171], v[192:195], v[34:37]
	v_mfma_f32_16x16x32_bf16 v[22:25], v[148:151], v[224:227], v[22:25]
	v_mfma_f32_16x16x32_bf16 v[18:21], v[168:171], v[224:227], v[18:21]
	v_mfma_f32_16x16x32_bf16 v[46:49], v[228:231], v[172:175], v[46:49]
	v_mfma_f32_16x16x32_bf16 v[42:45], v[236:239], v[172:175], v[42:45]
	v_mfma_f32_16x16x32_bf16 v[30:33], v[228:231], v[180:183], v[30:33]
	v_mfma_f32_16x16x32_bf16 v[26:29], v[236:239], v[180:183], v[26:29]
	v_mfma_f32_16x16x32_bf16 v[14:17], v[228:231], v[188:191], v[14:17]
	v_mfma_f32_16x16x32_bf16 v[10:13], v[236:239], v[188:191], v[10:13]
	v_mfma_f32_16x16x32_bf16 v[6:9], v[228:231], v[196:199], v[6:9]
	v_mfma_f32_16x16x32_bf16 v[2:5], v[236:239], v[196:199], v[2:5]
	v_mfma_f32_16x16x32_bf16 v[46:49], v[232:235], v[176:179], v[46:49]
	v_mfma_f32_16x16x32_bf16 v[42:45], v[240:243], v[176:179], v[42:45]
	v_mfma_f32_16x16x32_bf16 v[30:33], v[232:235], v[184:187], v[30:33]
	v_mfma_f32_16x16x32_bf16 v[26:29], v[240:243], v[184:187], v[26:29]
	v_mfma_f32_16x16x32_bf16 v[14:17], v[232:235], v[192:195], v[14:17]
	v_mfma_f32_16x16x32_bf16 v[10:13], v[240:243], v[192:195], v[10:13]
	v_mfma_f32_16x16x32_bf16 v[6:9], v[232:235], v[224:227], v[6:9]
	v_mfma_f32_16x16x32_bf16 v[2:5], v[240:243], v[224:227], v[2:5]
	s_barrier
	s_add_i32 s13, s13, 2
	s_add_u32 s46, s46, 0x100
	s_addc_u32 s47, s47, 0
	s_add_u32 s1, s1, 0x100
	s_addc_u32 s12, s12, 0
	s_cmp_gt_u32 s13, 29
	s_cbranch_scc0 .LBB0_234
	v_readlane_b32 s6, v255, 23
	v_lshl_add_u32 v150, s61, 8, v140
	v_lshl_or_b32 v144, s60, 8, v142
	v_readlane_b32 s7, v255, 24
	v_ashrrev_i32_e32 v145, 31, v144
	s_movk_i32 s1, 0x5800
	v_mov_b64_e32 v[146:147], s[6:7]
	v_cvt_pk_bf16_f32 v70, v70, v71
	v_cvt_pk_bf16_f32 v71, v72, v73
	v_cvt_pk_bf16_f32 v72, v66, v67
	v_add_u32_e32 v66, 0x80, v150
	v_mad_i64_i32 v[148:149], s[12:13], v150, s1, v[146:147]
	v_lshlrev_b64 v[144:145], 1, v[144:145]
	v_cvt_pk_bf16_f32 v110, v110, v111
	v_cvt_pk_bf16_f32 v111, v112, v113
	v_cvt_pk_bf16_f32 v112, v106, v107
	v_or_b32_e32 v106, 16, v150
	v_mad_i64_i32 v[66:67], s[12:13], v66, s1, v[146:147]
	v_cvt_pk_bf16_f32 v46, v46, v47
	v_cvt_pk_bf16_f32 v47, v48, v49
	v_cvt_pk_bf16_f32 v48, v42, v43
	v_add_u32_e32 v42, 0x90, v150
	v_lshl_add_u64 v[148:149], v[148:149], 0, v[144:145]
	v_cvt_pk_bf16_f32 v113, v108, v109
	v_mad_i64_i32 v[106:107], s[12:13], v106, s1, v[146:147]
	v_cvt_pk_bf16_f32 v94, v94, v95
	v_cvt_pk_bf16_f32 v95, v96, v97
	v_cvt_pk_bf16_f32 v96, v90, v91
	v_or_b32_e32 v90, 32, v150
	v_lshl_add_u64 v[66:67], v[66:67], 0, v[144:145]
	v_cvt_pk_bf16_f32 v49, v44, v45
	v_mad_i64_i32 v[42:43], s[12:13], v42, s1, v[146:147]
	v_cvt_pk_bf16_f32 v30, v30, v31
	v_cvt_pk_bf16_f32 v31, v32, v33
	v_cvt_pk_bf16_f32 v32, v26, v27
	v_add_u32_e32 v26, 0xa0, v150
	global_store_dwordx4 v[148:149], v[110:113], off offset:256
	v_cvt_pk_bf16_f32 v97, v92, v93
	v_mad_i64_i32 v[90:91], s[12:13], v90, s1, v[146:147]
	v_lshl_add_u64 v[110:111], v[106:107], 0, v[144:145]
	v_cvt_pk_bf16_f32 v78, v78, v79
	v_cvt_pk_bf16_f32 v79, v80, v81
	v_cvt_pk_bf16_f32 v80, v74, v75
	v_or_b32_e32 v74, 48, v150
	global_store_dwordx4 v[66:67], v[46:49], off offset:256
	v_cvt_pk_bf16_f32 v33, v28, v29
	v_mad_i64_i32 v[26:27], s[12:13], v26, s1, v[146:147]
	v_lshl_add_u64 v[46:47], v[42:43], 0, v[144:145]
	v_cvt_pk_bf16_f32 v14, v14, v15
	v_cvt_pk_bf16_f32 v15, v16, v17
	v_cvt_pk_bf16_f32 v16, v10, v11
	v_add_u32_e32 v10, 0xb0, v150
	global_store_dwordx4 v[110:111], v[94:97], off offset:256
	v_cvt_pk_bf16_f32 v81, v76, v77
	v_mad_i64_i32 v[74:75], s[12:13], v74, s1, v[146:147]
	v_lshl_add_u64 v[94:95], v[90:91], 0, v[144:145]
	global_store_dwordx4 v[46:47], v[30:33], off offset:256
	v_cvt_pk_bf16_f32 v17, v12, v13
	v_mad_i64_i32 v[10:11], s[12:13], v10, s1, v[146:147]
	v_lshl_add_u64 v[30:31], v[26:27], 0, v[144:145]
	v_cvt_pk_bf16_f32 v126, v126, v127
	v_cvt_pk_bf16_f32 v127, v128, v129
	v_cvt_pk_bf16_f32 v128, v122, v123
	v_cvt_pk_bf16_f32 v129, v124, v125
	v_cvt_pk_bf16_f32 v106, v118, v119
	v_cvt_pk_bf16_f32 v107, v120, v121
	v_cvt_pk_bf16_f32 v108, v114, v115
	v_cvt_pk_bf16_f32 v109, v116, v117
	v_cvt_pk_bf16_f32 v90, v102, v103
	v_cvt_pk_bf16_f32 v91, v104, v105
	v_cvt_pk_bf16_f32 v92, v98, v99
	v_cvt_pk_bf16_f32 v93, v100, v101
	global_store_dwordx4 v[94:95], v[78:81], off offset:256
	v_cvt_pk_bf16_f32 v76, v82, v83
	v_cvt_pk_bf16_f32 v77, v84, v85
	v_lshl_add_u64 v[78:79], v[74:75], 0, v[144:145]
	v_cvt_pk_bf16_f32 v74, v86, v87
	v_cvt_pk_bf16_f32 v75, v88, v89
	v_cvt_pk_bf16_f32 v73, v68, v69
	v_cvt_pk_bf16_f32 v62, v62, v63
	v_cvt_pk_bf16_f32 v63, v64, v65
	v_cvt_pk_bf16_f32 v64, v58, v59
	v_cvt_pk_bf16_f32 v65, v60, v61
	v_cvt_pk_bf16_f32 v42, v54, v55
	v_cvt_pk_bf16_f32 v43, v56, v57
	v_cvt_pk_bf16_f32 v44, v50, v51
	v_cvt_pk_bf16_f32 v45, v52, v53
	v_cvt_pk_bf16_f32 v26, v38, v39
	v_cvt_pk_bf16_f32 v27, v40, v41
	v_cvt_pk_bf16_f32 v28, v34, v35
	v_cvt_pk_bf16_f32 v29, v36, v37
	global_store_dwordx4 v[30:31], v[14:17], off offset:256
	v_cvt_pk_bf16_f32 v12, v18, v19
	v_cvt_pk_bf16_f32 v13, v20, v21
	v_lshl_add_u64 v[14:15], v[10:11], 0, v[144:145]
	v_cvt_pk_bf16_f32 v10, v22, v23
	v_cvt_pk_bf16_f32 v11, v24, v25
	v_cvt_pk_bf16_f32 v6, v6, v7
	v_cvt_pk_bf16_f32 v7, v8, v9
	v_cvt_pk_bf16_f32 v8, v2, v3
	v_cvt_pk_bf16_f32 v9, v4, v5
	s_and_b64 vcc, exec, s[40:41]
	s_mov_b32 s60, s0
	s_mov_b32 s61, s38
	s_mov_b64 s[48:49], s[44:45]
	s_mov_b64 s[46:47], s[42:43]
	global_store_dwordx4 v[148:149], v[126:129], off
	global_store_dwordx4 v[110:111], v[106:109], off
	global_store_dwordx4 v[94:95], v[90:93], off
	global_store_dwordx4 v[78:79], v[74:77], off
	global_store_dwordx4 v[78:79], v[70:73], off offset:256
	global_store_dwordx4 v[66:67], v[62:65], off
	global_store_dwordx4 v[46:47], v[42:45], off
	global_store_dwordx4 v[30:31], v[26:29], off
	global_store_dwordx4 v[14:15], v[10:13], off
	global_store_dwordx4 v[14:15], v[6:9], off offset:256
	s_cbranch_vccz .LBB0_227
	s_waitcnt vmcnt(0)
	v_readlane_b32 s60, v255, 21
	s_cmpk_gt_u32 s36, 0xff
	s_mov_b32 s18, s60
	v_readlane_b32 s61, v255, 22
	s_cbranch_scc1 .LBB0_238
	s_barrier

.LBB0_282:
	s_add_i32 s67, s50, 2
	s_add_u32 s51, s0, 0xfff80080
	s_addc_u32 s52, s1, -1
	s_add_i32 s68, 0, 0x10000
	ds_read_b128 v[136:139], v153
	ds_read_b128 v[140:143], v153 offset:1024
	ds_read_b128 v[144:147], v153 offset:2048
	ds_read_b128 v[148:151], v153 offset:3072
	s_cmp_eq_u32 s12, s50
	s_cselect_b32 s50, s48, s13
	s_cselect_b32 s53, s47, s52
	s_cselect_b32 s52, s46, s51
	s_cselect_b32 s51, s49, s66
	ds_read_b128 v[168:171], v155
	ds_read_b128 v[172:175], v155 offset:1024
	ds_read_b128 v[176:179], v155 offset:2048
	ds_read_b128 v[180:183], v155 offset:3072
	ds_read_b128 v[184:187], v155 offset:4096
	ds_read_b128 v[188:191], v155 offset:5120
	ds_read_b128 v[192:195], v155 offset:6144
	ds_read_b128 v[196:199], v155 offset:7168
	s_add_i32 m0, s55, 0xc000
	s_nop 0
	global_load_lds_dwordx4 v132, s[0:1]
	s_add_i32 m0, s55, 0xe000
	s_nop 0
	global_load_lds_dwordx4 v134, s[0:1]
	s_add_i32 s70, 0, 0x14000
	s_add_i32 s68, s68, s54
	ds_read_b128 v[224:227], v153 offset:16384
	ds_read_b128 v[228:231], v153 offset:17408
	ds_read_b128 v[232:235], v153 offset:18432
	ds_read_b128 v[236:239], v153 offset:19456
	s_waitcnt lgkmcnt(0)
	s_nop 0
	s_barrier
	v_mfma_f32_16x16x32_bf16 v[126:129], v[136:139], v[168:171], v[126:129]
	v_mfma_f32_16x16x32_bf16 v[122:125], v[144:147], v[168:171], v[122:125]
	v_mfma_f32_16x16x32_bf16 v[110:113], v[136:139], v[176:179], v[110:113]
	v_mfma_f32_16x16x32_bf16 v[106:109], v[144:147], v[176:179], v[106:109]
	v_mfma_f32_16x16x32_bf16 v[94:97], v[136:139], v[184:187], v[94:97]
	v_mfma_f32_16x16x32_bf16 v[90:93], v[144:147], v[184:187], v[90:93]
	v_mfma_f32_16x16x32_bf16 v[78:81], v[136:139], v[192:195], v[78:81]
	v_mfma_f32_16x16x32_bf16 v[74:77], v[144:147], v[192:195], v[74:77]
	v_mfma_f32_16x16x32_bf16 v[126:129], v[140:143], v[172:175], v[126:129]
	v_mfma_f32_16x16x32_bf16 v[122:125], v[148:151], v[172:175], v[122:125]
	v_mfma_f32_16x16x32_bf16 v[110:113], v[140:143], v[180:183], v[110:113]
	v_mfma_f32_16x16x32_bf16 v[106:109], v[148:151], v[180:183], v[106:109]
	v_mfma_f32_16x16x32_bf16 v[94:97], v[140:143], v[188:191], v[94:97]
	v_mfma_f32_16x16x32_bf16 v[90:93], v[148:151], v[188:191], v[90:93]
	v_mfma_f32_16x16x32_bf16 v[78:81], v[140:143], v[196:199], v[78:81]
	v_mfma_f32_16x16x32_bf16 v[74:77], v[148:151], v[196:199], v[74:77]
	v_mfma_f32_16x16x32_bf16 v[118:121], v[224:227], v[168:171], v[118:121]
	v_mfma_f32_16x16x32_bf16 v[114:117], v[232:235], v[168:171], v[114:117]
	v_mfma_f32_16x16x32_bf16 v[102:105], v[224:227], v[176:179], v[102:105]
	v_mfma_f32_16x16x32_bf16 v[98:101], v[232:235], v[176:179], v[98:101]
	v_mfma_f32_16x16x32_bf16 v[86:89], v[224:227], v[184:187], v[86:89]
	v_mfma_f32_16x16x32_bf16 v[82:85], v[232:235], v[184:187], v[82:85]
	v_mfma_f32_16x16x32_bf16 v[70:73], v[224:227], v[192:195], v[70:73]
	v_mfma_f32_16x16x32_bf16 v[66:69], v[232:235], v[192:195], v[66:69]
	v_mfma_f32_16x16x32_bf16 v[118:121], v[228:231], v[172:175], v[118:121]
	v_mfma_f32_16x16x32_bf16 v[114:117], v[236:239], v[172:175], v[114:117]
	v_mfma_f32_16x16x32_bf16 v[102:105], v[228:231], v[180:183], v[102:105]
	v_mfma_f32_16x16x32_bf16 v[98:101], v[236:239], v[180:183], v[98:101]
	v_mfma_f32_16x16x32_bf16 v[86:89], v[228:231], v[188:191], v[86:89]
	v_mfma_f32_16x16x32_bf16 v[82:85], v[236:239], v[188:191], v[82:85]
	v_mfma_f32_16x16x32_bf16 v[70:73], v[228:231], v[196:199], v[70:73]
	v_mfma_f32_16x16x32_bf16 v[66:69], v[236:239], v[196:199], v[66:69]
	s_barrier
	s_mov_b32 m0, s55
	s_add_u32 s78, s52, s94
	s_addc_u32 s79, s53, s95
	ds_read_b128 v[168:171], v155 offset:16384
	ds_read_b128 v[172:175], v155 offset:17408
	ds_read_b128 v[176:179], v155 offset:18432
	ds_read_b128 v[180:183], v155 offset:19456
	ds_read_b128 v[184:187], v155 offset:20480
	ds_read_b128 v[188:191], v155 offset:21504
	ds_read_b128 v[192:195], v155 offset:22528
	ds_read_b128 v[196:199], v155 offset:23552
	global_load_lds_dwordx4 v0, s[52:53]
	s_mov_b32 m0, s56
	s_nop 0
	global_load_lds_dwordx4 v130, s[52:53]
	s_add_u32 s76, s50, s94
	s_addc_u32 s77, s51, s95
	s_mov_b32 m0, s68
	s_nop 0
	global_load_lds_dwordx4 v0, s[50:51]
	s_add_i32 m0, s68, 0x2000
	s_nop 0
	global_load_lds_dwordx4 v130, s[50:51]
	s_add_u32 s68, s50, 0x80000
	s_addc_u32 s69, s51, 0
	s_add_i32 s70, s70, s54
	s_mov_b32 m0, s70
	s_nop 0
	global_load_lds_dwordx4 v0, s[68:69]
	s_add_i32 m0, s70, 0x2000
	s_nop 0
	global_load_lds_dwordx4 v130, s[68:69]
	s_waitcnt vmcnt(6) lgkmcnt(0)
	s_barrier
	v_mfma_f32_16x16x32_bf16 v[62:65], v[136:139], v[168:171], v[62:65]
	v_mfma_f32_16x16x32_bf16 v[58:61], v[144:147], v[168:171], v[58:61]
	v_mfma_f32_16x16x32_bf16 v[46:49], v[136:139], v[176:179], v[46:49]
	v_mfma_f32_16x16x32_bf16 v[42:45], v[144:147], v[176:179], v[42:45]
	v_mfma_f32_16x16x32_bf16 v[30:33], v[136:139], v[184:187], v[30:33]
	v_mfma_f32_16x16x32_bf16 v[26:29], v[144:147], v[184:187], v[26:29]
	v_mfma_f32_16x16x32_bf16 v[14:17], v[136:139], v[192:195], v[14:17]
	v_mfma_f32_16x16x32_bf16 v[10:13], v[144:147], v[192:195], v[10:13]
	v_mfma_f32_16x16x32_bf16 v[62:65], v[140:143], v[172:175], v[62:65]
	v_mfma_f32_16x16x32_bf16 v[58:61], v[148:151], v[172:175], v[58:61]
	v_mfma_f32_16x16x32_bf16 v[46:49], v[140:143], v[180:183], v[46:49]
	v_mfma_f32_16x16x32_bf16 v[42:45], v[148:151], v[180:183], v[42:45]
	v_mfma_f32_16x16x32_bf16 v[30:33], v[140:143], v[188:191], v[30:33]
	v_mfma_f32_16x16x32_bf16 v[26:29], v[148:151], v[188:191], v[26:29]
	v_mfma_f32_16x16x32_bf16 v[14:17], v[140:143], v[196:199], v[14:17]
	v_mfma_f32_16x16x32_bf16 v[10:13], v[148:151], v[196:199], v[10:13]
	v_mfma_f32_16x16x32_bf16 v[54:57], v[224:227], v[168:171], v[54:57]
	v_mfma_f32_16x16x32_bf16 v[50:53], v[232:235], v[168:171], v[50:53]
	v_mfma_f32_16x16x32_bf16 v[38:41], v[224:227], v[176:179], v[38:41]
	v_mfma_f32_16x16x32_bf16 v[34:37], v[232:235], v[176:179], v[34:37]
	v_mfma_f32_16x16x32_bf16 v[22:25], v[224:227], v[184:187], v[22:25]
	v_mfma_f32_16x16x32_bf16 v[18:21], v[232:235], v[184:187], v[18:21]
	v_mfma_f32_16x16x32_bf16 v[6:9], v[224:227], v[192:195], v[6:9]
	v_mfma_f32_16x16x32_bf16 v[2:5], v[232:235], v[192:195], v[2:5]
	v_mfma_f32_16x16x32_bf16 v[54:57], v[228:231], v[172:175], v[54:57]
	v_mfma_f32_16x16x32_bf16 v[50:53], v[236:239], v[172:175], v[50:53]
	v_mfma_f32_16x16x32_bf16 v[38:41], v[228:231], v[180:183], v[38:41]
	v_mfma_f32_16x16x32_bf16 v[34:37], v[236:239], v[180:183], v[34:37]
	v_mfma_f32_16x16x32_bf16 v[22:25], v[228:231], v[188:191], v[22:25]
	v_mfma_f32_16x16x32_bf16 v[18:21], v[236:239], v[188:191], v[18:21]
	v_mfma_f32_16x16x32_bf16 v[6:9], v[228:231], v[196:199], v[6:9]
	v_mfma_f32_16x16x32_bf16 v[2:5], v[236:239], v[196:199], v[2:5]
	s_barrier
	s_add_i32 s68, 0, 0x18000
	ds_read_b128 v[136:139], v153 offset:32768
	ds_read_b128 v[140:143], v153 offset:33792
	ds_read_b128 v[144:147], v153 offset:34816
	ds_read_b128 v[148:151], v153 offset:35840
	s_add_u32 s52, s52, 0x80000
	s_addc_u32 s53, s53, 0
	ds_read_b128 v[168:171], v155 offset:32768
	ds_read_b128 v[172:175], v155 offset:33792
	ds_read_b128 v[176:179], v155 offset:34816
	ds_read_b128 v[180:183], v155 offset:35840
	ds_read_b128 v[184:187], v155 offset:36864
	ds_read_b128 v[188:191], v155 offset:37888
	ds_read_b128 v[192:195], v155 offset:38912
	ds_read_b128 v[196:199], v155 offset:39936
	s_mov_b32 m0, s57
	s_nop 0
	global_load_lds_dwordx4 v0, s[52:53]
	s_mov_b32 m0, s58
	s_nop 0
	global_load_lds_dwordx4 v130, s[52:53]
	s_add_i32 s52, 0, 0x1c000
	s_add_i32 s53, s68, s54
	ds_read_b128 v[224:227], v153 offset:49152
	ds_read_b128 v[228:231], v153 offset:50176
	ds_read_b128 v[232:235], v153 offset:51200
	ds_read_b128 v[236:239], v153 offset:52224
	s_waitcnt lgkmcnt(0)
	s_nop 0
	s_barrier
	v_mfma_f32_16x16x32_bf16 v[126:129], v[136:139], v[168:171], v[126:129]
	v_mfma_f32_16x16x32_bf16 v[122:125], v[144:147], v[168:171], v[122:125]
	v_mfma_f32_16x16x32_bf16 v[110:113], v[136:139], v[176:179], v[110:113]
	v_mfma_f32_16x16x32_bf16 v[106:109], v[144:147], v[176:179], v[106:109]
	v_mfma_f32_16x16x32_bf16 v[94:97], v[136:139], v[184:187], v[94:97]
	v_mfma_f32_16x16x32_bf16 v[90:93], v[144:147], v[184:187], v[90:93]
	v_mfma_f32_16x16x32_bf16 v[78:81], v[136:139], v[192:195], v[78:81]
	v_mfma_f32_16x16x32_bf16 v[74:77], v[144:147], v[192:195], v[74:77]
	v_mfma_f32_16x16x32_bf16 v[126:129], v[140:143], v[172:175], v[126:129]
	v_mfma_f32_16x16x32_bf16 v[122:125], v[148:151], v[172:175], v[122:125]
	v_mfma_f32_16x16x32_bf16 v[110:113], v[140:143], v[180:183], v[110:113]
	v_mfma_f32_16x16x32_bf16 v[106:109], v[148:151], v[180:183], v[106:109]
	v_mfma_f32_16x16x32_bf16 v[94:97], v[140:143], v[188:191], v[94:97]
	v_mfma_f32_16x16x32_bf16 v[90:93], v[148:151], v[188:191], v[90:93]
	v_mfma_f32_16x16x32_bf16 v[78:81], v[140:143], v[196:199], v[78:81]
	v_mfma_f32_16x16x32_bf16 v[74:77], v[148:151], v[196:199], v[74:77]
	v_mfma_f32_16x16x32_bf16 v[118:121], v[224:227], v[168:171], v[118:121]
	v_mfma_f32_16x16x32_bf16 v[114:117], v[232:235], v[168:171], v[114:117]
	v_mfma_f32_16x16x32_bf16 v[102:105], v[224:227], v[176:179], v[102:105]
	v_mfma_f32_16x16x32_bf16 v[98:101], v[232:235], v[176:179], v[98:101]
	v_mfma_f32_16x16x32_bf16 v[86:89], v[224:227], v[184:187], v[86:89]
	v_mfma_f32_16x16x32_bf16 v[82:85], v[232:235], v[184:187], v[82:85]
	v_mfma_f32_16x16x32_bf16 v[70:73], v[224:227], v[192:195], v[70:73]
	v_mfma_f32_16x16x32_bf16 v[66:69], v[232:235], v[192:195], v[66:69]
	v_mfma_f32_16x16x32_bf16 v[118:121], v[228:231], v[172:175], v[118:121]
	v_mfma_f32_16x16x32_bf16 v[114:117], v[236:239], v[172:175], v[114:117]
	v_mfma_f32_16x16x32_bf16 v[102:105], v[228:231], v[180:183], v[102:105]
	v_mfma_f32_16x16x32_bf16 v[98:101], v[236:239], v[180:183], v[98:101]
	v_mfma_f32_16x16x32_bf16 v[86:89], v[228:231], v[188:191], v[86:89]
	v_mfma_f32_16x16x32_bf16 v[82:85], v[236:239], v[188:191], v[82:85]
	v_mfma_f32_16x16x32_bf16 v[70:73], v[228:231], v[196:199], v[70:73]
	v_mfma_f32_16x16x32_bf16 v[66:69], v[236:239], v[196:199], v[66:69]
	s_barrier
	s_mov_b32 m0, s59
	ds_read_b128 v[168:171], v155 offset:49152
	ds_read_b128 v[172:175], v155 offset:50176
	ds_read_b128 v[176:179], v155 offset:51200
	ds_read_b128 v[180:183], v155 offset:52224
	ds_read_b128 v[184:187], v155 offset:53248
	ds_read_b128 v[188:191], v155 offset:54272
	ds_read_b128 v[192:195], v155 offset:55296
	ds_read_b128 v[196:199], v155 offset:56320
	global_load_lds_dwordx4 v0, s[78:79]
	s_mov_b32 m0, s60
	s_nop 0
	global_load_lds_dwordx4 v130, s[78:79]
	s_mov_b32 m0, s53
	s_nop 0
	global_load_lds_dwordx4 v0, s[76:77]
	s_add_i32 m0, s53, 0x2000
	s_nop 0
	global_load_lds_dwordx4 v130, s[76:77]
	s_add_u32 s50, s50, 0x80080
	s_addc_u32 s51, s51, 0
	s_add_i32 s52, s52, s54
	s_mov_b32 m0, s52
	s_nop 0
	global_load_lds_dwordx4 v0, s[50:51]
	s_add_i32 m0, s52, 0x2000
	s_nop 0
	global_load_lds_dwordx4 v130, s[50:51]
	s_waitcnt vmcnt(6) lgkmcnt(0)
	s_barrier
	v_mfma_f32_16x16x32_bf16 v[62:65], v[136:139], v[168:171], v[62:65]
	v_mfma_f32_16x16x32_bf16 v[58:61], v[144:147], v[168:171], v[58:61]
	v_mfma_f32_16x16x32_bf16 v[46:49], v[136:139], v[176:179], v[46:49]
	v_mfma_f32_16x16x32_bf16 v[42:45], v[144:147], v[176:179], v[42:45]
	v_mfma_f32_16x16x32_bf16 v[30:33], v[136:139], v[184:187], v[30:33]
	v_mfma_f32_16x16x32_bf16 v[26:29], v[144:147], v[184:187], v[26:29]
	v_mfma_f32_16x16x32_bf16 v[14:17], v[136:139], v[192:195], v[14:17]
	v_mfma_f32_16x16x32_bf16 v[10:13], v[144:147], v[192:195], v[10:13]
	v_mfma_f32_16x16x32_bf16 v[62:65], v[140:143], v[172:175], v[62:65]
	v_mfma_f32_16x16x32_bf16 v[58:61], v[148:151], v[172:175], v[58:61]
	v_mfma_f32_16x16x32_bf16 v[46:49], v[140:143], v[180:183], v[46:49]
	v_mfma_f32_16x16x32_bf16 v[42:45], v[148:151], v[180:183], v[42:45]
	v_mfma_f32_16x16x32_bf16 v[30:33], v[140:143], v[188:191], v[30:33]
	v_mfma_f32_16x16x32_bf16 v[26:29], v[148:151], v[188:191], v[26:29]
	v_mfma_f32_16x16x32_bf16 v[14:17], v[140:143], v[196:199], v[14:17]
	v_mfma_f32_16x16x32_bf16 v[10:13], v[148:151], v[196:199], v[10:13]
	v_mfma_f32_16x16x32_bf16 v[54:57], v[224:227], v[168:171], v[54:57]
	v_mfma_f32_16x16x32_bf16 v[50:53], v[232:235], v[168:171], v[50:53]
	v_mfma_f32_16x16x32_bf16 v[38:41], v[224:227], v[176:179], v[38:41]
	v_mfma_f32_16x16x32_bf16 v[34:37], v[232:235], v[176:179], v[34:37]
	v_mfma_f32_16x16x32_bf16 v[22:25], v[224:227], v[184:187], v[22:25]
	v_mfma_f32_16x16x32_bf16 v[18:21], v[232:235], v[184:187], v[18:21]
	v_mfma_f32_16x16x32_bf16 v[6:9], v[224:227], v[192:195], v[6:9]
	v_mfma_f32_16x16x32_bf16 v[2:5], v[232:235], v[192:195], v[2:5]
	v_mfma_f32_16x16x32_bf16 v[54:57], v[228:231], v[172:175], v[54:57]
	v_mfma_f32_16x16x32_bf16 v[50:53], v[236:239], v[172:175], v[50:53]
	v_mfma_f32_16x16x32_bf16 v[38:41], v[228:231], v[180:183], v[38:41]
	v_mfma_f32_16x16x32_bf16 v[34:37], v[236:239], v[180:183], v[34:37]
	v_mfma_f32_16x16x32_bf16 v[22:25], v[228:231], v[188:191], v[22:25]
	v_mfma_f32_16x16x32_bf16 v[18:21], v[236:239], v[188:191], v[18:21]
	v_mfma_f32_16x16x32_bf16 v[6:9], v[228:231], v[196:199], v[6:9]
	v_mfma_f32_16x16x32_bf16 v[2:5], v[236:239], v[196:199], v[2:5]
	s_barrier
	s_add_u32 s0, s0, 0x100
	s_addc_u32 s1, s1, 0
	s_add_u32 s13, s13, 0x100
	s_addc_u32 s66, s66, 0
	s_mov_b32 s50, s67
	s_cmp_ge_i32 s67, s41
	s_cbranch_scc0 .LBB0_282
	s_cmp_eq_u32 s63, 2
	s_cbranch_scc1 .Lepi6_orig
	v_readlane_b32 s90, v255, 17
	v_readlane_b32 s91, v255, 18
	v_readlane_b32 s96, v255, 19
	v_readlane_b32 s97, v255, 20
	v_readlane_b32 s8, v255, 25
	v_readlane_b32 s9, v255, 26
	v_readlane_b32 s68, v253, 58
	v_readlane_b32 s69, v253, 59
	v_lshl_or_b32 v156, s64, 8, v154
	v_lshlrev_b32_e32 v156, 2, v156
	v_lshl_add_u32 v157, v152, 13, v156
	s_lshl_b32 s72, s65, 21
	s_add_u32 s74, s68, s72
	s_addc_u32 s75, s69, 0
	s_add_u32 s76, s22, s72
	s_addc_u32 s77, s23, 0
	s_lshr_b32 s73, s65, 3
	s_mul_i32 s73, s73, 0xc000
	s_add_u32 s73, s73, 0x4000
	s_add_u32 s70, s90, s73
	s_addc_u32 s71, s91, 0
	global_load_dwordx4 v[140:143], v156, s[70:71]
	global_load_dwordx4 v[144:147], v156, s[70:71] offset:64
	global_load_dwordx4 v[148:151], v156, s[70:71] offset:512
	global_load_dwordx4 v[168:171], v156, s[70:71] offset:576
	global_load_dwordx4 v[224:227], v157, s[74:75] nt
	global_load_dwordx4 v[228:231], v157, s[74:75] offset:64 nt
	global_load_dwordx4 v[232:235], v157, s[74:75] offset:512 nt
	global_load_dwordx4 v[236:239], v157, s[74:75] offset:576 nt
	s_add_u32 s74, s74, 0x20000
	s_addc_u32 s75, s75, 0
	global_load_dwordx4 v[240:243], v157, s[74:75] nt
	global_load_dwordx4 v[244:247], v157, s[74:75] offset:64 nt
	s_waitcnt vmcnt(5)
	v_pk_fma_f32 v[128:129], v[128:129], v[142:143], v[226:227]
	v_pk_fma_f32 v[126:127], v[126:127], v[140:141], v[224:225]
	global_store_dwordx4 v157, v[126:129], s[76:77]
	global_load_dwordx4 v[224:227], v157, s[74:75] offset:512 nt
	s_waitcnt vmcnt(6)
	v_pk_fma_f32 v[124:125], v[124:125], v[146:147], v[230:231]
	v_pk_fma_f32 v[122:123], v[122:123], v[144:145], v[228:229]
	global_store_dwordx4 v157, v[122:125], s[76:77] offset:64
	global_load_dwordx4 v[228:231], v157, s[74:75] offset:576 nt
	s_waitcnt vmcnt(7)
	v_pk_fma_f32 v[120:121], v[120:121], v[150:151], v[234:235]
	v_pk_fma_f32 v[118:119], v[118:119], v[148:149], v[232:233]
	global_store_dwordx4 v157, v[118:121], s[76:77] offset:512
	s_add_u32 s74, s74, 0x20000
	s_addc_u32 s75, s75, 0
	global_load_dwordx4 v[232:235], v157, s[74:75] nt
	s_waitcnt vmcnt(8)
	v_pk_fma_f32 v[116:117], v[116:117], v[170:171], v[238:239]
	v_pk_fma_f32 v[114:115], v[114:115], v[168:169], v[236:237]
	global_store_dwordx4 v157, v[114:117], s[76:77] offset:576
	global_load_dwordx4 v[236:239], v157, s[74:75] offset:64 nt
	s_add_u32 s76, s76, 0x20000
	s_addc_u32 s77, s77, 0
	s_waitcnt vmcnt(9)
	v_pk_fma_f32 v[112:113], v[112:113], v[142:143], v[242:243]
	v_pk_fma_f32 v[110:111], v[110:111], v[140:141], v[240:241]
	global_store_dwordx4 v157, v[110:113], s[76:77]
	global_load_dwordx4 v[240:243], v157, s[74:75] offset:512 nt
	s_waitcnt vmcnt(10)
	v_pk_fma_f32 v[108:109], v[108:109], v[146:147], v[246:247]
	v_pk_fma_f32 v[106:107], v[106:107], v[144:145], v[244:245]
	global_store_dwordx4 v157, v[106:109], s[76:77] offset:64
	global_load_dwordx4 v[244:247], v157, s[74:75] offset:576 nt
	s_waitcnt vmcnt(10)
	v_pk_fma_f32 v[104:105], v[104:105], v[150:151], v[226:227]
	v_pk_fma_f32 v[102:103], v[102:103], v[148:149], v[224:225]
	global_store_dwordx4 v157, v[102:105], s[76:77] offset:512
	s_add_u32 s74, s74, 0x20000
	s_addc_u32 s75, s75, 0
	global_load_dwordx4 v[224:227], v157, s[74:75] nt
	s_waitcnt vmcnt(10)
	v_pk_fma_f32 v[100:101], v[100:101], v[170:171], v[230:231]
	v_pk_fma_f32 v[98:99], v[98:99], v[168:169], v[228:229]
	global_store_dwordx4 v157, v[98:101], s[76:77] offset:576
	global_load_dwordx4 v[228:231], v157, s[74:75] offset:64 nt
	s_add_u32 s76, s76, 0x20000
	s_addc_u32 s77, s77, 0
	s_waitcnt vmcnt(10)
	v_pk_fma_f32 v[96:97], v[96:97], v[142:143], v[234:235]
	v_pk_fma_f32 v[94:95], v[94:95], v[140:141], v[232:233]
	global_store_dwordx4 v157, v[94:97], s[76:77]
	global_load_dwordx4 v[232:235], v157, s[74:75] offset:512 nt
	s_waitcnt vmcnt(10)
	v_pk_fma_f32 v[92:93], v[92:93], v[146:147], v[238:239]
	v_pk_fma_f32 v[90:91], v[90:91], v[144:145], v[236:237]
	global_store_dwordx4 v157, v[90:93], s[76:77] offset:64
	global_load_dwordx4 v[236:239], v157, s[74:75] offset:576 nt
	s_waitcnt vmcnt(10)
	v_pk_fma_f32 v[88:89], v[88:89], v[150:151], v[242:243]
	v_pk_fma_f32 v[86:87], v[86:87], v[148:149], v[240:241]
	global_store_dwordx4 v157, v[86:89], s[76:77] offset:512
	s_add_u32 s74, s74, 0xa0000
	s_addc_u32 s75, s75, 0
	global_load_dwordx4 v[240:243], v157, s[74:75] nt
	s_waitcnt vmcnt(10)
	v_pk_fma_f32 v[84:85], v[84:85], v[170:171], v[246:247]
	v_pk_fma_f32 v[82:83], v[82:83], v[168:169], v[244:245]
	global_store_dwordx4 v157, v[82:85], s[76:77] offset:576
	global_load_dwordx4 v[244:247], v157, s[74:75] offset:64 nt
	s_add_u32 s76, s76, 0x20000
	s_addc_u32 s77, s77, 0
	s_waitcnt vmcnt(10)
	v_pk_fma_f32 v[80:81], v[80:81], v[142:143], v[226:227]
	v_pk_fma_f32 v[78:79], v[78:79], v[140:141], v[224:225]
	global_store_dwordx4 v157, v[78:81], s[76:77]
	global_load_dwordx4 v[224:227], v157, s[74:75] offset:512 nt
	s_waitcnt vmcnt(10)
	v_pk_fma_f32 v[76:77], v[76:77], v[146:147], v[230:231]
	v_pk_fma_f32 v[74:75], v[74:75], v[144:145], v[228:229]
	global_store_dwordx4 v157, v[74:77], s[76:77] offset:64
	global_load_dwordx4 v[228:231], v157, s[74:75] offset:576 nt
	s_waitcnt vmcnt(10)
	v_pk_fma_f32 v[72:73], v[72:73], v[150:151], v[234:235]
	v_pk_fma_f32 v[70:71], v[70:71], v[148:149], v[232:233]
	global_store_dwordx4 v157, v[70:73], s[76:77] offset:512
	s_add_u32 s74, s74, 0x20000
	s_addc_u32 s75, s75, 0
	global_load_dwordx4 v[232:235], v157, s[74:75] nt
	s_waitcnt vmcnt(10)
	v_pk_fma_f32 v[68:69], v[68:69], v[170:171], v[238:239]
	v_pk_fma_f32 v[66:67], v[66:67], v[168:169], v[236:237]
	global_store_dwordx4 v157, v[66:69], s[76:77] offset:576
	global_load_dwordx4 v[236:239], v157, s[74:75] offset:64 nt
	s_add_u32 s76, s76, 0xa0000
	s_addc_u32 s77, s77, 0
	s_waitcnt vmcnt(10)
	v_pk_fma_f32 v[64:65], v[64:65], v[142:143], v[242:243]
	v_pk_fma_f32 v[62:63], v[62:63], v[140:141], v[240:241]
	global_store_dwordx4 v157, v[62:65], s[76:77]
	global_load_dwordx4 v[240:243], v157, s[74:75] offset:512 nt
	s_waitcnt vmcnt(10)
	v_pk_fma_f32 v[60:61], v[60:61], v[146:147], v[246:247]
	v_pk_fma_f32 v[58:59], v[58:59], v[144:145], v[244:245]
	global_store_dwordx4 v157, v[58:61], s[76:77] offset:64
	global_load_dwordx4 v[244:247], v157, s[74:75] offset:576 nt
	s_waitcnt vmcnt(10)
	v_pk_fma_f32 v[56:57], v[56:57], v[150:151], v[226:227]
	v_pk_fma_f32 v[54:55], v[54:55], v[148:149], v[224:225]
	global_store_dwordx4 v157, v[54:57], s[76:77] offset:512
	s_add_u32 s74, s74, 0x20000
	s_addc_u32 s75, s75, 0
	global_load_dwordx4 v[224:227], v157, s[74:75] nt
	s_waitcnt vmcnt(10)
	v_pk_fma_f32 v[52:53], v[52:53], v[170:171], v[230:231]
	v_pk_fma_f32 v[50:51], v[50:51], v[168:169], v[228:229]
	global_store_dwordx4 v157, v[50:53], s[76:77] offset:576
	global_load_dwordx4 v[228:231], v157, s[74:75] offset:64 nt
	s_add_u32 s76, s76, 0x20000
	s_addc_u32 s77, s77, 0
	s_waitcnt vmcnt(10)
	v_pk_fma_f32 v[48:49], v[48:49], v[142:143], v[234:235]
	v_pk_fma_f32 v[46:47], v[46:47], v[140:141], v[232:233]
	global_store_dwordx4 v157, v[46:49], s[76:77]
	global_load_dwordx4 v[232:235], v157, s[74:75] offset:512 nt
	s_waitcnt vmcnt(10)
	v_pk_fma_f32 v[44:45], v[44:45], v[146:147], v[238:239]
	v_pk_fma_f32 v[42:43], v[42:43], v[144:145], v[236:237]
	global_store_dwordx4 v157, v[42:45], s[76:77] offset:64
	global_load_dwordx4 v[236:239], v157, s[74:75] offset:576 nt
	s_waitcnt vmcnt(10)
	v_pk_fma_f32 v[40:41], v[40:41], v[150:151], v[242:243]
	v_pk_fma_f32 v[38:39], v[38:39], v[148:149], v[240:241]
	global_store_dwordx4 v157, v[38:41], s[76:77] offset:512
	s_add_u32 s74, s74, 0x20000
	s_addc_u32 s75, s75, 0
	global_load_dwordx4 v[240:243], v157, s[74:75] nt
	s_waitcnt vmcnt(10)
	v_pk_fma_f32 v[36:37], v[36:37], v[170:171], v[246:247]
	v_pk_fma_f32 v[34:35], v[34:35], v[168:169], v[244:245]
	global_store_dwordx4 v157, v[34:37], s[76:77] offset:576
	global_load_dwordx4 v[244:247], v157, s[74:75] offset:64 nt
	s_add_u32 s76, s76, 0x20000
	s_addc_u32 s77, s77, 0
	s_waitcnt vmcnt(10)
	v_pk_fma_f32 v[32:33], v[32:33], v[142:143], v[226:227]
	v_pk_fma_f32 v[30:31], v[30:31], v[140:141], v[224:225]
	global_store_dwordx4 v157, v[30:33], s[76:77]
	global_load_dwordx4 v[224:227], v157, s[74:75] offset:512 nt
	s_waitcnt vmcnt(10)
	v_pk_fma_f32 v[28:29], v[28:29], v[146:147], v[230:231]
	v_pk_fma_f32 v[26:27], v[26:27], v[144:145], v[228:229]
	global_store_dwordx4 v157, v[26:29], s[76:77] offset:64
	global_load_dwordx4 v[228:231], v157, s[74:75] offset:576 nt
	s_waitcnt vmcnt(10)
	v_pk_fma_f32 v[24:25], v[24:25], v[150:151], v[234:235]
	v_pk_fma_f32 v[22:23], v[22:23], v[148:149], v[232:233]
	global_store_dwordx4 v157, v[22:25], s[76:77] offset:512
	s_waitcnt vmcnt(9)
	v_pk_fma_f32 v[20:21], v[20:21], v[170:171], v[238:239]
	v_pk_fma_f32 v[18:19], v[18:19], v[168:169], v[236:237]
	global_store_dwordx4 v157, v[18:21], s[76:77] offset:576
	s_add_u32 s76, s76, 0x20000
	s_addc_u32 s77, s77, 0
	s_waitcnt vmcnt(8)
	v_pk_fma_f32 v[16:17], v[16:17], v[142:143], v[242:243]
	v_pk_fma_f32 v[14:15], v[14:15], v[140:141], v[240:241]
	global_store_dwordx4 v157, v[14:17], s[76:77]
	s_waitcnt vmcnt(7)
	v_pk_fma_f32 v[12:13], v[12:13], v[146:147], v[246:247]
	v_pk_fma_f32 v[10:11], v[10:11], v[144:145], v[244:245]
	global_store_dwordx4 v157, v[10:13], s[76:77] offset:64
	s_waitcnt vmcnt(6)
	v_pk_fma_f32 v[8:9], v[8:9], v[150:151], v[226:227]
	v_pk_fma_f32 v[6:7], v[6:7], v[148:149], v[224:225]
	global_store_dwordx4 v157, v[6:9], s[76:77] offset:512
	s_waitcnt vmcnt(5)
	v_pk_fma_f32 v[4:5], v[4:5], v[170:171], v[230:231]
	v_pk_fma_f32 v[2:3], v[2:3], v[168:169], v[228:229]
	global_store_dwordx4 v157, v[2:5], s[76:77] offset:576
	s_branch .LBB0_269

.LBB0_572:
	s_add_u32 s41, s46, 0xfff80080
	s_addc_u32 s48, s47, -1
	s_add_i32 s64, 0, 0x10000
	ds_read_b128 v[144:147], v141
	ds_read_b128 v[148:151], v141 offset:1024
	ds_read_b128 v[152:155], v141 offset:2048
	ds_read_b128 v[168:171], v141 offset:3072
	s_cmp_eq_u32 s39, 28
	s_cselect_b32 s51, s43, s48
	s_cselect_b32 s50, s42, s41
	s_cselect_b32 s49, s45, s13
	s_cselect_b32 s48, s44, s12
	ds_read_b128 v[172:175], v143
	ds_read_b128 v[176:179], v143 offset:1024
	ds_read_b128 v[180:183], v143 offset:2048
	ds_read_b128 v[184:187], v143 offset:3072
	ds_read_b128 v[188:191], v143 offset:4096
	ds_read_b128 v[192:195], v143 offset:5120
	ds_read_b128 v[196:199], v143 offset:6144
	ds_read_b128 v[224:227], v143 offset:7168
	s_add_i32 m0, s54, 0xc000
	s_nop 0
	global_load_lds_dwordx4 v136, s[46:47]
	s_add_i32 m0, s54, 0xe000
	s_nop 0
	global_load_lds_dwordx4 v138, s[46:47]
	s_add_i32 s41, 0, 0x14000
	s_add_i32 s64, s64, s53
	ds_read_b128 v[228:231], v141 offset:16384
	ds_read_b128 v[232:235], v141 offset:17408
	ds_read_b128 v[236:239], v141 offset:18432
	ds_read_b128 v[240:243], v141 offset:19456
	s_waitcnt lgkmcnt(0)
	s_nop 0
	s_barrier
	v_mfma_f32_16x16x32_bf16 v[126:129], v[144:147], v[172:175], v[126:129]
	v_mfma_f32_16x16x32_bf16 v[122:125], v[152:155], v[172:175], v[122:125]
	v_mfma_f32_16x16x32_bf16 v[118:121], v[144:147], v[180:183], v[118:121]
	v_mfma_f32_16x16x32_bf16 v[114:117], v[152:155], v[180:183], v[114:117]
	v_mfma_f32_16x16x32_bf16 v[102:105], v[144:147], v[188:191], v[102:105]
	v_mfma_f32_16x16x32_bf16 v[98:101], v[152:155], v[188:191], v[98:101]
	v_mfma_f32_16x16x32_bf16 v[86:89], v[144:147], v[196:199], v[86:89]
	v_mfma_f32_16x16x32_bf16 v[82:85], v[152:155], v[196:199], v[82:85]
	v_mfma_f32_16x16x32_bf16 v[126:129], v[148:151], v[176:179], v[126:129]
	v_mfma_f32_16x16x32_bf16 v[122:125], v[168:171], v[176:179], v[122:125]
	v_mfma_f32_16x16x32_bf16 v[118:121], v[148:151], v[184:187], v[118:121]
	v_mfma_f32_16x16x32_bf16 v[114:117], v[168:171], v[184:187], v[114:117]
	v_mfma_f32_16x16x32_bf16 v[102:105], v[148:151], v[192:195], v[102:105]
	v_mfma_f32_16x16x32_bf16 v[98:101], v[168:171], v[192:195], v[98:101]
	v_mfma_f32_16x16x32_bf16 v[86:89], v[148:151], v[224:227], v[86:89]
	v_mfma_f32_16x16x32_bf16 v[82:85], v[168:171], v[224:227], v[82:85]
	v_mfma_f32_16x16x32_bf16 v[110:113], v[228:231], v[172:175], v[110:113]
	v_mfma_f32_16x16x32_bf16 v[106:109], v[236:239], v[172:175], v[106:109]
	v_mfma_f32_16x16x32_bf16 v[94:97], v[228:231], v[180:183], v[94:97]
	v_mfma_f32_16x16x32_bf16 v[90:93], v[236:239], v[180:183], v[90:93]
	v_mfma_f32_16x16x32_bf16 v[78:81], v[228:231], v[188:191], v[78:81]
	v_mfma_f32_16x16x32_bf16 v[74:77], v[236:239], v[188:191], v[74:77]
	v_mfma_f32_16x16x32_bf16 v[70:73], v[228:231], v[196:199], v[70:73]
	v_mfma_f32_16x16x32_bf16 v[66:69], v[236:239], v[196:199], v[66:69]
	v_mfma_f32_16x16x32_bf16 v[110:113], v[232:235], v[176:179], v[110:113]
	v_mfma_f32_16x16x32_bf16 v[106:109], v[240:243], v[176:179], v[106:109]
	v_mfma_f32_16x16x32_bf16 v[94:97], v[232:235], v[184:187], v[94:97]
	v_mfma_f32_16x16x32_bf16 v[90:93], v[240:243], v[184:187], v[90:93]
	v_mfma_f32_16x16x32_bf16 v[78:81], v[232:235], v[192:195], v[78:81]
	v_mfma_f32_16x16x32_bf16 v[74:77], v[240:243], v[192:195], v[74:77]
	v_mfma_f32_16x16x32_bf16 v[70:73], v[232:235], v[224:227], v[70:73]
	v_mfma_f32_16x16x32_bf16 v[66:69], v[240:243], v[224:227], v[66:69]
	s_barrier
	s_mov_b32 m0, s54
	s_add_u32 s78, s50, s94
	s_addc_u32 s79, s51, s95
	ds_read_b128 v[172:175], v143 offset:16384
	ds_read_b128 v[176:179], v143 offset:17408
	ds_read_b128 v[180:183], v143 offset:18432
	ds_read_b128 v[184:187], v143 offset:19456
	ds_read_b128 v[188:191], v143 offset:20480
	ds_read_b128 v[192:195], v143 offset:21504
	ds_read_b128 v[196:199], v143 offset:22528
	ds_read_b128 v[224:227], v143 offset:23552
	global_load_lds_dwordx4 v130, s[50:51]
	s_mov_b32 m0, s55
	s_nop 0
	global_load_lds_dwordx4 v132, s[50:51]
	s_add_u32 s76, s48, s94
	s_addc_u32 s77, s49, s95
	s_mov_b32 m0, s64
	s_nop 0
	global_load_lds_dwordx4 v0, s[48:49]
	s_add_i32 m0, s64, 0x2000
	s_nop 0
	global_load_lds_dwordx4 v134, s[48:49]
	s_add_u32 s64, s48, 0x80000
	s_addc_u32 s65, s49, 0
	s_add_i32 s41, s41, s53
	s_mov_b32 m0, s41
	s_nop 0
	global_load_lds_dwordx4 v0, s[64:65]
	s_add_i32 m0, s41, 0x2000
	s_nop 0
	global_load_lds_dwordx4 v134, s[64:65]
	s_waitcnt vmcnt(6) lgkmcnt(0)
	s_barrier
	v_mfma_f32_16x16x32_bf16 v[62:65], v[144:147], v[172:175], v[62:65]
	v_mfma_f32_16x16x32_bf16 v[58:61], v[152:155], v[172:175], v[58:61]
	v_mfma_f32_16x16x32_bf16 v[54:57], v[144:147], v[180:183], v[54:57]
	v_mfma_f32_16x16x32_bf16 v[50:53], v[152:155], v[180:183], v[50:53]
	v_mfma_f32_16x16x32_bf16 v[38:41], v[144:147], v[188:191], v[38:41]
	v_mfma_f32_16x16x32_bf16 v[34:37], v[152:155], v[188:191], v[34:37]
	v_mfma_f32_16x16x32_bf16 v[22:25], v[144:147], v[196:199], v[22:25]
	v_mfma_f32_16x16x32_bf16 v[18:21], v[152:155], v[196:199], v[18:21]
	v_mfma_f32_16x16x32_bf16 v[62:65], v[148:151], v[176:179], v[62:65]
	v_mfma_f32_16x16x32_bf16 v[58:61], v[168:171], v[176:179], v[58:61]
	v_mfma_f32_16x16x32_bf16 v[54:57], v[148:151], v[184:187], v[54:57]
	v_mfma_f32_16x16x32_bf16 v[50:53], v[168:171], v[184:187], v[50:53]
	v_mfma_f32_16x16x32_bf16 v[38:41], v[148:151], v[192:195], v[38:41]
	v_mfma_f32_16x16x32_bf16 v[34:37], v[168:171], v[192:195], v[34:37]
	v_mfma_f32_16x16x32_bf16 v[22:25], v[148:151], v[224:227], v[22:25]
	v_mfma_f32_16x16x32_bf16 v[18:21], v[168:171], v[224:227], v[18:21]
	v_mfma_f32_16x16x32_bf16 v[46:49], v[228:231], v[172:175], v[46:49]
	v_mfma_f32_16x16x32_bf16 v[42:45], v[236:239], v[172:175], v[42:45]
	v_mfma_f32_16x16x32_bf16 v[30:33], v[228:231], v[180:183], v[30:33]
	v_mfma_f32_16x16x32_bf16 v[26:29], v[236:239], v[180:183], v[26:29]
	v_mfma_f32_16x16x32_bf16 v[14:17], v[228:231], v[188:191], v[14:17]
	v_mfma_f32_16x16x32_bf16 v[10:13], v[236:239], v[188:191], v[10:13]
	v_mfma_f32_16x16x32_bf16 v[6:9], v[228:231], v[196:199], v[6:9]
	v_mfma_f32_16x16x32_bf16 v[2:5], v[236:239], v[196:199], v[2:5]
	v_mfma_f32_16x16x32_bf16 v[46:49], v[232:235], v[176:179], v[46:49]
	v_mfma_f32_16x16x32_bf16 v[42:45], v[240:243], v[176:179], v[42:45]
	v_mfma_f32_16x16x32_bf16 v[30:33], v[232:235], v[184:187], v[30:33]
	v_mfma_f32_16x16x32_bf16 v[26:29], v[240:243], v[184:187], v[26:29]
	v_mfma_f32_16x16x32_bf16 v[14:17], v[232:235], v[192:195], v[14:17]
	v_mfma_f32_16x16x32_bf16 v[10:13], v[240:243], v[192:195], v[10:13]
	v_mfma_f32_16x16x32_bf16 v[6:9], v[232:235], v[224:227], v[6:9]
	v_mfma_f32_16x16x32_bf16 v[2:5], v[240:243], v[224:227], v[2:5]
	s_barrier
	s_add_i32 s41, 0, 0x18000
	ds_read_b128 v[144:147], v141 offset:32768
	ds_read_b128 v[148:151], v141 offset:33792
	ds_read_b128 v[152:155], v141 offset:34816
	ds_read_b128 v[168:171], v141 offset:35840
	s_add_u32 s50, s50, 0x80000
	s_addc_u32 s51, s51, 0
	ds_read_b128 v[172:175], v143 offset:32768
	ds_read_b128 v[176:179], v143 offset:33792
	ds_read_b128 v[180:183], v143 offset:34816
	ds_read_b128 v[184:187], v143 offset:35840
	ds_read_b128 v[188:191], v143 offset:36864
	ds_read_b128 v[192:195], v143 offset:37888
	ds_read_b128 v[196:199], v143 offset:38912
	ds_read_b128 v[224:227], v143 offset:39936
	s_mov_b32 m0, s56
	s_nop 0
	global_load_lds_dwordx4 v130, s[50:51]
	s_mov_b32 m0, s57
	s_nop 0
	global_load_lds_dwordx4 v132, s[50:51]
	s_add_i32 s50, 0, 0x1c000
	s_add_i32 s41, s41, s53
	ds_read_b128 v[228:231], v141 offset:49152
	ds_read_b128 v[232:235], v141 offset:50176
	ds_read_b128 v[236:239], v141 offset:51200
	ds_read_b128 v[240:243], v141 offset:52224
	s_waitcnt lgkmcnt(0)
	s_nop 0
	s_barrier
	v_mfma_f32_16x16x32_bf16 v[126:129], v[144:147], v[172:175], v[126:129]
	v_mfma_f32_16x16x32_bf16 v[122:125], v[152:155], v[172:175], v[122:125]
	v_mfma_f32_16x16x32_bf16 v[118:121], v[144:147], v[180:183], v[118:121]
	v_mfma_f32_16x16x32_bf16 v[114:117], v[152:155], v[180:183], v[114:117]
	v_mfma_f32_16x16x32_bf16 v[102:105], v[144:147], v[188:191], v[102:105]
	v_mfma_f32_16x16x32_bf16 v[98:101], v[152:155], v[188:191], v[98:101]
	v_mfma_f32_16x16x32_bf16 v[86:89], v[144:147], v[196:199], v[86:89]
	v_mfma_f32_16x16x32_bf16 v[82:85], v[152:155], v[196:199], v[82:85]
	v_mfma_f32_16x16x32_bf16 v[126:129], v[148:151], v[176:179], v[126:129]
	v_mfma_f32_16x16x32_bf16 v[122:125], v[168:171], v[176:179], v[122:125]
	v_mfma_f32_16x16x32_bf16 v[118:121], v[148:151], v[184:187], v[118:121]
	v_mfma_f32_16x16x32_bf16 v[114:117], v[168:171], v[184:187], v[114:117]
	v_mfma_f32_16x16x32_bf16 v[102:105], v[148:151], v[192:195], v[102:105]
	v_mfma_f32_16x16x32_bf16 v[98:101], v[168:171], v[192:195], v[98:101]
	v_mfma_f32_16x16x32_bf16 v[86:89], v[148:151], v[224:227], v[86:89]
	v_mfma_f32_16x16x32_bf16 v[82:85], v[168:171], v[224:227], v[82:85]
	v_mfma_f32_16x16x32_bf16 v[110:113], v[228:231], v[172:175], v[110:113]
	v_mfma_f32_16x16x32_bf16 v[106:109], v[236:239], v[172:175], v[106:109]
	v_mfma_f32_16x16x32_bf16 v[94:97], v[228:231], v[180:183], v[94:97]
	v_mfma_f32_16x16x32_bf16 v[90:93], v[236:239], v[180:183], v[90:93]
	v_mfma_f32_16x16x32_bf16 v[78:81], v[228:231], v[188:191], v[78:81]
	v_mfma_f32_16x16x32_bf16 v[74:77], v[236:239], v[188:191], v[74:77]
	v_mfma_f32_16x16x32_bf16 v[70:73], v[228:231], v[196:199], v[70:73]
	v_mfma_f32_16x16x32_bf16 v[66:69], v[236:239], v[196:199], v[66:69]
	v_mfma_f32_16x16x32_bf16 v[110:113], v[232:235], v[176:179], v[110:113]
	v_mfma_f32_16x16x32_bf16 v[106:109], v[240:243], v[176:179], v[106:109]
	v_mfma_f32_16x16x32_bf16 v[94:97], v[232:235], v[184:187], v[94:97]
	v_mfma_f32_16x16x32_bf16 v[90:93], v[240:243], v[184:187], v[90:93]
	v_mfma_f32_16x16x32_bf16 v[78:81], v[232:235], v[192:195], v[78:81]
	v_mfma_f32_16x16x32_bf16 v[74:77], v[240:243], v[192:195], v[74:77]
	v_mfma_f32_16x16x32_bf16 v[70:73], v[232:235], v[224:227], v[70:73]
	v_mfma_f32_16x16x32_bf16 v[66:69], v[240:243], v[224:227], v[66:69]
	s_barrier
	s_mov_b32 m0, s59
	ds_read_b128 v[172:175], v143 offset:49152
	ds_read_b128 v[176:179], v143 offset:50176
	ds_read_b128 v[180:183], v143 offset:51200
	ds_read_b128 v[184:187], v143 offset:52224
	ds_read_b128 v[188:191], v143 offset:53248
	ds_read_b128 v[192:195], v143 offset:54272
	ds_read_b128 v[196:199], v143 offset:55296
	ds_read_b128 v[224:227], v143 offset:56320
	global_load_lds_dwordx4 v130, s[78:79]
	s_mov_b32 m0, s60
	s_nop 0
	global_load_lds_dwordx4 v132, s[78:79]
	s_mov_b32 m0, s41
	s_nop 0
	global_load_lds_dwordx4 v0, s[76:77]
	s_add_i32 m0, s41, 0x2000
	s_nop 0
	global_load_lds_dwordx4 v134, s[76:77]
	s_add_u32 s48, s48, 0x80080
	s_addc_u32 s49, s49, 0
	s_add_i32 s41, s50, s53
	s_mov_b32 m0, s41
	s_nop 0
	global_load_lds_dwordx4 v0, s[48:49]
	s_add_i32 m0, s41, 0x2000
	s_nop 0
	global_load_lds_dwordx4 v134, s[48:49]
	s_waitcnt vmcnt(6) lgkmcnt(0)
	s_barrier
	v_mfma_f32_16x16x32_bf16 v[62:65], v[144:147], v[172:175], v[62:65]
	v_mfma_f32_16x16x32_bf16 v[58:61], v[152:155], v[172:175], v[58:61]
	v_mfma_f32_16x16x32_bf16 v[54:57], v[144:147], v[180:183], v[54:57]
	v_mfma_f32_16x16x32_bf16 v[50:53], v[152:155], v[180:183], v[50:53]
	v_mfma_f32_16x16x32_bf16 v[38:41], v[144:147], v[188:191], v[38:41]
	v_mfma_f32_16x16x32_bf16 v[34:37], v[152:155], v[188:191], v[34:37]
	v_mfma_f32_16x16x32_bf16 v[22:25], v[144:147], v[196:199], v[22:25]
	v_mfma_f32_16x16x32_bf16 v[18:21], v[152:155], v[196:199], v[18:21]
	v_mfma_f32_16x16x32_bf16 v[62:65], v[148:151], v[176:179], v[62:65]
	v_mfma_f32_16x16x32_bf16 v[58:61], v[168:171], v[176:179], v[58:61]
	v_mfma_f32_16x16x32_bf16 v[54:57], v[148:151], v[184:187], v[54:57]
	v_mfma_f32_16x16x32_bf16 v[50:53], v[168:171], v[184:187], v[50:53]
	v_mfma_f32_16x16x32_bf16 v[38:41], v[148:151], v[192:195], v[38:41]
	v_mfma_f32_16x16x32_bf16 v[34:37], v[168:171], v[192:195], v[34:37]
	v_mfma_f32_16x16x32_bf16 v[22:25], v[148:151], v[224:227], v[22:25]
	v_mfma_f32_16x16x32_bf16 v[18:21], v[168:171], v[224:227], v[18:21]
	v_mfma_f32_16x16x32_bf16 v[46:49], v[228:231], v[172:175], v[46:49]
	v_mfma_f32_16x16x32_bf16 v[42:45], v[236:239], v[172:175], v[42:45]
	v_mfma_f32_16x16x32_bf16 v[30:33], v[228:231], v[180:183], v[30:33]
	v_mfma_f32_16x16x32_bf16 v[26:29], v[236:239], v[180:183], v[26:29]
	v_mfma_f32_16x16x32_bf16 v[14:17], v[228:231], v[188:191], v[14:17]
	v_mfma_f32_16x16x32_bf16 v[10:13], v[236:239], v[188:191], v[10:13]
	v_mfma_f32_16x16x32_bf16 v[6:9], v[228:231], v[196:199], v[6:9]
	v_mfma_f32_16x16x32_bf16 v[2:5], v[236:239], v[196:199], v[2:5]
	v_mfma_f32_16x16x32_bf16 v[46:49], v[232:235], v[176:179], v[46:49]
	v_mfma_f32_16x16x32_bf16 v[42:45], v[240:243], v[176:179], v[42:45]
	v_mfma_f32_16x16x32_bf16 v[30:33], v[232:235], v[184:187], v[30:33]
	v_mfma_f32_16x16x32_bf16 v[26:29], v[240:243], v[184:187], v[26:29]
	v_mfma_f32_16x16x32_bf16 v[14:17], v[232:235], v[192:195], v[14:17]
	v_mfma_f32_16x16x32_bf16 v[10:13], v[240:243], v[192:195], v[10:13]
	v_mfma_f32_16x16x32_bf16 v[6:9], v[232:235], v[224:227], v[6:9]
	v_mfma_f32_16x16x32_bf16 v[2:5], v[240:243], v[224:227], v[2:5]
	s_barrier
	s_add_i32 s39, s39, 2
	s_add_u32 s46, s46, 0x100
	s_addc_u32 s47, s47, 0
	s_add_u32 s12, s12, 0x100
	s_addc_u32 s13, s13, 0
	s_cmp_gt_u32 s39, 29
	s_cbranch_scc0 .LBB0_572
	s_cmp_lg_u32 s62, 0
	s_cbranch_scc0 .LBB0_575
	s_lshl_b32 s39, s61, 8
	s_mov_b64 s[12:13], 0
	s_branch .LBB0_576

.LBB0_788:
	s_add_u32 s39, s46, 0xfff80080
	s_addc_u32 s48, s47, -1
	s_add_i32 s64, 0, 0x10000
	ds_read_b128 v[144:147], v141
	ds_read_b128 v[148:151], v141 offset:1024
	ds_read_b128 v[152:155], v141 offset:2048
	ds_read_b128 v[168:171], v141 offset:3072
	s_cmp_eq_u32 s13, 28
	s_cselect_b32 s51, s43, s48
	s_cselect_b32 s50, s42, s39
	s_cselect_b32 s49, s45, s12
	s_cselect_b32 s48, s44, s1
	ds_read_b128 v[172:175], v143
	ds_read_b128 v[176:179], v143 offset:1024
	ds_read_b128 v[180:183], v143 offset:2048
	ds_read_b128 v[184:187], v143 offset:3072
	ds_read_b128 v[188:191], v143 offset:4096
	ds_read_b128 v[192:195], v143 offset:5120
	ds_read_b128 v[196:199], v143 offset:6144
	ds_read_b128 v[224:227], v143 offset:7168
	s_add_i32 m0, s54, 0xc000
	s_nop 0
	global_load_lds_dwordx4 v136, s[46:47]
	s_add_i32 m0, s54, 0xe000
	s_nop 0
	global_load_lds_dwordx4 v138, s[46:47]
	s_add_i32 s39, 0, 0x14000
	s_add_i32 s64, s64, s53
	ds_read_b128 v[228:231], v141 offset:16384
	ds_read_b128 v[232:235], v141 offset:17408
	ds_read_b128 v[236:239], v141 offset:18432
	ds_read_b128 v[240:243], v141 offset:19456
	s_waitcnt lgkmcnt(0)
	s_barrier
	v_mfma_f32_16x16x32_bf16 v[126:129], v[144:147], v[172:175], v[126:129]
	v_mfma_f32_16x16x32_bf16 v[122:125], v[152:155], v[172:175], v[122:125]
	v_mfma_f32_16x16x32_bf16 v[118:121], v[144:147], v[180:183], v[118:121]
	v_mfma_f32_16x16x32_bf16 v[114:117], v[152:155], v[180:183], v[114:117]
	v_mfma_f32_16x16x32_bf16 v[102:105], v[144:147], v[188:191], v[102:105]
	v_mfma_f32_16x16x32_bf16 v[98:101], v[152:155], v[188:191], v[98:101]
	v_mfma_f32_16x16x32_bf16 v[86:89], v[144:147], v[196:199], v[86:89]
	v_mfma_f32_16x16x32_bf16 v[82:85], v[152:155], v[196:199], v[82:85]
	v_mfma_f32_16x16x32_bf16 v[126:129], v[148:151], v[176:179], v[126:129]
	v_mfma_f32_16x16x32_bf16 v[122:125], v[168:171], v[176:179], v[122:125]
	v_mfma_f32_16x16x32_bf16 v[118:121], v[148:151], v[184:187], v[118:121]
	v_mfma_f32_16x16x32_bf16 v[114:117], v[168:171], v[184:187], v[114:117]
	v_mfma_f32_16x16x32_bf16 v[102:105], v[148:151], v[192:195], v[102:105]
	v_mfma_f32_16x16x32_bf16 v[98:101], v[168:171], v[192:195], v[98:101]
	v_mfma_f32_16x16x32_bf16 v[86:89], v[148:151], v[224:227], v[86:89]
	v_mfma_f32_16x16x32_bf16 v[82:85], v[168:171], v[224:227], v[82:85]
	v_mfma_f32_16x16x32_bf16 v[110:113], v[228:231], v[172:175], v[110:113]
	v_mfma_f32_16x16x32_bf16 v[106:109], v[236:239], v[172:175], v[106:109]
	v_mfma_f32_16x16x32_bf16 v[94:97], v[228:231], v[180:183], v[94:97]
	v_mfma_f32_16x16x32_bf16 v[90:93], v[236:239], v[180:183], v[90:93]
	v_mfma_f32_16x16x32_bf16 v[78:81], v[228:231], v[188:191], v[78:81]
	v_mfma_f32_16x16x32_bf16 v[74:77], v[236:239], v[188:191], v[74:77]
	v_mfma_f32_16x16x32_bf16 v[70:73], v[228:231], v[196:199], v[70:73]
	v_mfma_f32_16x16x32_bf16 v[66:69], v[236:239], v[196:199], v[66:69]
	v_mfma_f32_16x16x32_bf16 v[110:113], v[232:235], v[176:179], v[110:113]
	v_mfma_f32_16x16x32_bf16 v[106:109], v[240:243], v[176:179], v[106:109]
	v_mfma_f32_16x16x32_bf16 v[94:97], v[232:235], v[184:187], v[94:97]
	v_mfma_f32_16x16x32_bf16 v[90:93], v[240:243], v[184:187], v[90:93]
	v_mfma_f32_16x16x32_bf16 v[78:81], v[232:235], v[192:195], v[78:81]
	v_mfma_f32_16x16x32_bf16 v[74:77], v[240:243], v[192:195], v[74:77]
	v_mfma_f32_16x16x32_bf16 v[70:73], v[232:235], v[224:227], v[70:73]
	v_mfma_f32_16x16x32_bf16 v[66:69], v[240:243], v[224:227], v[66:69]
	s_barrier
	s_mov_b32 m0, s54
	s_add_u32 s78, s50, s94
	s_addc_u32 s79, s51, s95
	ds_read_b128 v[172:175], v143 offset:16384
	ds_read_b128 v[176:179], v143 offset:17408
	ds_read_b128 v[180:183], v143 offset:18432
	ds_read_b128 v[184:187], v143 offset:19456
	ds_read_b128 v[188:191], v143 offset:20480
	ds_read_b128 v[192:195], v143 offset:21504
	ds_read_b128 v[196:199], v143 offset:22528
	ds_read_b128 v[224:227], v143 offset:23552
	global_load_lds_dwordx4 v130, s[50:51]
	s_mov_b32 m0, s55
	s_nop 0
	global_load_lds_dwordx4 v132, s[50:51]
	s_add_u32 s76, s48, s94
	s_addc_u32 s77, s49, s95
	s_mov_b32 m0, s64
	s_nop 0
	global_load_lds_dwordx4 v0, s[48:49]
	s_add_i32 m0, s64, 0x2000
	s_nop 0
	global_load_lds_dwordx4 v134, s[48:49]
	s_add_u32 s64, s48, 0x80000
	s_addc_u32 s65, s49, 0
	s_add_i32 s39, s39, s53
	s_mov_b32 m0, s39
	s_nop 0
	global_load_lds_dwordx4 v0, s[64:65]
	s_add_i32 m0, s39, 0x2000
	s_nop 0
	global_load_lds_dwordx4 v134, s[64:65]
	s_waitcnt vmcnt(6) lgkmcnt(0)
	s_barrier
	v_mfma_f32_16x16x32_bf16 v[62:65], v[144:147], v[172:175], v[62:65]
	v_mfma_f32_16x16x32_bf16 v[58:61], v[152:155], v[172:175], v[58:61]
	v_mfma_f32_16x16x32_bf16 v[54:57], v[144:147], v[180:183], v[54:57]
	v_mfma_f32_16x16x32_bf16 v[50:53], v[152:155], v[180:183], v[50:53]
	v_mfma_f32_16x16x32_bf16 v[38:41], v[144:147], v[188:191], v[38:41]
	v_mfma_f32_16x16x32_bf16 v[34:37], v[152:155], v[188:191], v[34:37]
	v_mfma_f32_16x16x32_bf16 v[22:25], v[144:147], v[196:199], v[22:25]
	v_mfma_f32_16x16x32_bf16 v[18:21], v[152:155], v[196:199], v[18:21]
	v_mfma_f32_16x16x32_bf16 v[62:65], v[148:151], v[176:179], v[62:65]
	v_mfma_f32_16x16x32_bf16 v[58:61], v[168:171], v[176:179], v[58:61]
	v_mfma_f32_16x16x32_bf16 v[54:57], v[148:151], v[184:187], v[54:57]
	v_mfma_f32_16x16x32_bf16 v[50:53], v[168:171], v[184:187], v[50:53]
	v_mfma_f32_16x16x32_bf16 v[38:41], v[148:151], v[192:195], v[38:41]
	v_mfma_f32_16x16x32_bf16 v[34:37], v[168:171], v[192:195], v[34:37]
	v_mfma_f32_16x16x32_bf16 v[22:25], v[148:151], v[224:227], v[22:25]
	v_mfma_f32_16x16x32_bf16 v[18:21], v[168:171], v[224:227], v[18:21]
	v_mfma_f32_16x16x32_bf16 v[46:49], v[228:231], v[172:175], v[46:49]
	v_mfma_f32_16x16x32_bf16 v[42:45], v[236:239], v[172:175], v[42:45]
	v_mfma_f32_16x16x32_bf16 v[30:33], v[228:231], v[180:183], v[30:33]
	v_mfma_f32_16x16x32_bf16 v[26:29], v[236:239], v[180:183], v[26:29]
	v_mfma_f32_16x16x32_bf16 v[14:17], v[228:231], v[188:191], v[14:17]
	v_mfma_f32_16x16x32_bf16 v[10:13], v[236:239], v[188:191], v[10:13]
	v_mfma_f32_16x16x32_bf16 v[6:9], v[228:231], v[196:199], v[6:9]
	v_mfma_f32_16x16x32_bf16 v[2:5], v[236:239], v[196:199], v[2:5]
	v_mfma_f32_16x16x32_bf16 v[46:49], v[232:235], v[176:179], v[46:49]
	v_mfma_f32_16x16x32_bf16 v[42:45], v[240:243], v[176:179], v[42:45]
	v_mfma_f32_16x16x32_bf16 v[30:33], v[232:235], v[184:187], v[30:33]
	v_mfma_f32_16x16x32_bf16 v[26:29], v[240:243], v[184:187], v[26:29]
	v_mfma_f32_16x16x32_bf16 v[14:17], v[232:235], v[192:195], v[14:17]
	v_mfma_f32_16x16x32_bf16 v[10:13], v[240:243], v[192:195], v[10:13]
	v_mfma_f32_16x16x32_bf16 v[6:9], v[232:235], v[224:227], v[6:9]
	v_mfma_f32_16x16x32_bf16 v[2:5], v[240:243], v[224:227], v[2:5]
	s_barrier
	s_add_i32 s39, 0, 0x18000
	ds_read_b128 v[144:147], v141 offset:32768
	ds_read_b128 v[148:151], v141 offset:33792
	ds_read_b128 v[152:155], v141 offset:34816
	ds_read_b128 v[168:171], v141 offset:35840
	s_add_u32 s50, s50, 0x80000
	s_addc_u32 s51, s51, 0
	ds_read_b128 v[172:175], v143 offset:32768
	ds_read_b128 v[176:179], v143 offset:33792
	ds_read_b128 v[180:183], v143 offset:34816
	ds_read_b128 v[184:187], v143 offset:35840
	ds_read_b128 v[188:191], v143 offset:36864
	ds_read_b128 v[192:195], v143 offset:37888
	ds_read_b128 v[196:199], v143 offset:38912
	ds_read_b128 v[224:227], v143 offset:39936
	s_mov_b32 m0, s56
	s_nop 0
	global_load_lds_dwordx4 v130, s[50:51]
	s_mov_b32 m0, s57
	s_nop 0
	global_load_lds_dwordx4 v132, s[50:51]
	s_add_i32 s50, 0, 0x1c000
	s_add_i32 s39, s39, s53
	ds_read_b128 v[228:231], v141 offset:49152
	ds_read_b128 v[232:235], v141 offset:50176
	ds_read_b128 v[236:239], v141 offset:51200
	ds_read_b128 v[240:243], v141 offset:52224
	s_waitcnt lgkmcnt(0)
	s_nop 0
	s_barrier
	v_mfma_f32_16x16x32_bf16 v[126:129], v[144:147], v[172:175], v[126:129]
	v_mfma_f32_16x16x32_bf16 v[122:125], v[152:155], v[172:175], v[122:125]
	v_mfma_f32_16x16x32_bf16 v[118:121], v[144:147], v[180:183], v[118:121]
	v_mfma_f32_16x16x32_bf16 v[114:117], v[152:155], v[180:183], v[114:117]
	v_mfma_f32_16x16x32_bf16 v[102:105], v[144:147], v[188:191], v[102:105]
	v_mfma_f32_16x16x32_bf16 v[98:101], v[152:155], v[188:191], v[98:101]
	v_mfma_f32_16x16x32_bf16 v[86:89], v[144:147], v[196:199], v[86:89]
	v_mfma_f32_16x16x32_bf16 v[82:85], v[152:155], v[196:199], v[82:85]
	v_mfma_f32_16x16x32_bf16 v[126:129], v[148:151], v[176:179], v[126:129]
	v_mfma_f32_16x16x32_bf16 v[122:125], v[168:171], v[176:179], v[122:125]
	v_mfma_f32_16x16x32_bf16 v[118:121], v[148:151], v[184:187], v[118:121]
	v_mfma_f32_16x16x32_bf16 v[114:117], v[168:171], v[184:187], v[114:117]
	v_mfma_f32_16x16x32_bf16 v[102:105], v[148:151], v[192:195], v[102:105]
	v_mfma_f32_16x16x32_bf16 v[98:101], v[168:171], v[192:195], v[98:101]
	v_mfma_f32_16x16x32_bf16 v[86:89], v[148:151], v[224:227], v[86:89]
	v_mfma_f32_16x16x32_bf16 v[82:85], v[168:171], v[224:227], v[82:85]
	v_mfma_f32_16x16x32_bf16 v[110:113], v[228:231], v[172:175], v[110:113]
	v_mfma_f32_16x16x32_bf16 v[106:109], v[236:239], v[172:175], v[106:109]
	v_mfma_f32_16x16x32_bf16 v[94:97], v[228:231], v[180:183], v[94:97]
	v_mfma_f32_16x16x32_bf16 v[90:93], v[236:239], v[180:183], v[90:93]
	v_mfma_f32_16x16x32_bf16 v[78:81], v[228:231], v[188:191], v[78:81]
	v_mfma_f32_16x16x32_bf16 v[74:77], v[236:239], v[188:191], v[74:77]
	v_mfma_f32_16x16x32_bf16 v[70:73], v[228:231], v[196:199], v[70:73]
	v_mfma_f32_16x16x32_bf16 v[66:69], v[236:239], v[196:199], v[66:69]
	v_mfma_f32_16x16x32_bf16 v[110:113], v[232:235], v[176:179], v[110:113]
	v_mfma_f32_16x16x32_bf16 v[106:109], v[240:243], v[176:179], v[106:109]
	v_mfma_f32_16x16x32_bf16 v[94:97], v[232:235], v[184:187], v[94:97]
	v_mfma_f32_16x16x32_bf16 v[90:93], v[240:243], v[184:187], v[90:93]
	v_mfma_f32_16x16x32_bf16 v[78:81], v[232:235], v[192:195], v[78:81]
	v_mfma_f32_16x16x32_bf16 v[74:77], v[240:243], v[192:195], v[74:77]
	v_mfma_f32_16x16x32_bf16 v[70:73], v[232:235], v[224:227], v[70:73]
	v_mfma_f32_16x16x32_bf16 v[66:69], v[240:243], v[224:227], v[66:69]
	s_barrier
	s_mov_b32 m0, s59
	ds_read_b128 v[172:175], v143 offset:49152
	ds_read_b128 v[176:179], v143 offset:50176
	ds_read_b128 v[180:183], v143 offset:51200
	ds_read_b128 v[184:187], v143 offset:52224
	ds_read_b128 v[188:191], v143 offset:53248
	ds_read_b128 v[192:195], v143 offset:54272
	ds_read_b128 v[196:199], v143 offset:55296
	ds_read_b128 v[224:227], v143 offset:56320
	global_load_lds_dwordx4 v130, s[78:79]
	s_mov_b32 m0, s61
	s_nop 0
	global_load_lds_dwordx4 v132, s[78:79]
	s_mov_b32 m0, s39
	s_nop 0
	global_load_lds_dwordx4 v0, s[76:77]
	s_add_i32 m0, s39, 0x2000
	s_nop 0
	global_load_lds_dwordx4 v134, s[76:77]
	s_add_u32 s48, s48, 0x80080
	s_addc_u32 s49, s49, 0
	s_add_i32 s39, s50, s53
	s_mov_b32 m0, s39
	s_nop 0
	global_load_lds_dwordx4 v0, s[48:49]
	s_add_i32 m0, s39, 0x2000
	s_nop 0
	global_load_lds_dwordx4 v134, s[48:49]
	s_waitcnt vmcnt(6) lgkmcnt(0)
	s_barrier
	v_mfma_f32_16x16x32_bf16 v[62:65], v[144:147], v[172:175], v[62:65]
	v_mfma_f32_16x16x32_bf16 v[58:61], v[152:155], v[172:175], v[58:61]
	v_mfma_f32_16x16x32_bf16 v[54:57], v[144:147], v[180:183], v[54:57]
	v_mfma_f32_16x16x32_bf16 v[50:53], v[152:155], v[180:183], v[50:53]
	v_mfma_f32_16x16x32_bf16 v[38:41], v[144:147], v[188:191], v[38:41]
	v_mfma_f32_16x16x32_bf16 v[34:37], v[152:155], v[188:191], v[34:37]
	v_mfma_f32_16x16x32_bf16 v[22:25], v[144:147], v[196:199], v[22:25]
	v_mfma_f32_16x16x32_bf16 v[18:21], v[152:155], v[196:199], v[18:21]
	v_mfma_f32_16x16x32_bf16 v[62:65], v[148:151], v[176:179], v[62:65]
	v_mfma_f32_16x16x32_bf16 v[58:61], v[168:171], v[176:179], v[58:61]
	v_mfma_f32_16x16x32_bf16 v[54:57], v[148:151], v[184:187], v[54:57]
	v_mfma_f32_16x16x32_bf16 v[50:53], v[168:171], v[184:187], v[50:53]
	v_mfma_f32_16x16x32_bf16 v[38:41], v[148:151], v[192:195], v[38:41]
	v_mfma_f32_16x16x32_bf16 v[34:37], v[168:171], v[192:195], v[34:37]
	v_mfma_f32_16x16x32_bf16 v[22:25], v[148:151], v[224:227], v[22:25]
	v_mfma_f32_16x16x32_bf16 v[18:21], v[168:171], v[224:227], v[18:21]
	v_mfma_f32_16x16x32_bf16 v[46:49], v[228:231], v[172:175], v[46:49]
	v_mfma_f32_16x16x32_bf16 v[42:45], v[236:239], v[172:175], v[42:45]
	v_mfma_f32_16x16x32_bf16 v[30:33], v[228:231], v[180:183], v[30:33]
	v_mfma_f32_16x16x32_bf16 v[26:29], v[236:239], v[180:183], v[26:29]
	v_mfma_f32_16x16x32_bf16 v[14:17], v[228:231], v[188:191], v[14:17]
	v_mfma_f32_16x16x32_bf16 v[10:13], v[236:239], v[188:191], v[10:13]
	v_mfma_f32_16x16x32_bf16 v[6:9], v[228:231], v[196:199], v[6:9]
	v_mfma_f32_16x16x32_bf16 v[2:5], v[236:239], v[196:199], v[2:5]
	v_mfma_f32_16x16x32_bf16 v[46:49], v[232:235], v[176:179], v[46:49]
	v_mfma_f32_16x16x32_bf16 v[42:45], v[240:243], v[176:179], v[42:45]
	v_mfma_f32_16x16x32_bf16 v[30:33], v[232:235], v[184:187], v[30:33]
	v_mfma_f32_16x16x32_bf16 v[26:29], v[240:243], v[184:187], v[26:29]
	v_mfma_f32_16x16x32_bf16 v[14:17], v[232:235], v[192:195], v[14:17]
	v_mfma_f32_16x16x32_bf16 v[10:13], v[240:243], v[192:195], v[10:13]
	v_mfma_f32_16x16x32_bf16 v[6:9], v[232:235], v[224:227], v[6:9]
	v_mfma_f32_16x16x32_bf16 v[2:5], v[240:243], v[224:227], v[2:5]
	s_barrier
	s_add_i32 s13, s13, 2
	s_add_u32 s46, s46, 0x100
	s_addc_u32 s47, s47, 0
	s_add_u32 s1, s1, 0x100
	s_addc_u32 s12, s12, 0
	s_cmp_gt_u32 s13, 29
	s_cbranch_scc0 .LBB0_788
	s_cmp_lg_u32 s62, 0
	s_cbranch_scc0 .LBB0_791
	s_lshl_b32 s1, s60, 8
	s_mov_b64 s[12:13], 0
	s_branch .LBB0_792
